# layer 1's adaLN GEMV moved from phase 0 into layer 0's mix phase (hand-written GEMV item on blocks 256..351)
# speedup vs baseline: 1.0913x; 1.0097x over previous
.LBB0_11:
	s_sub_u32 s0, s58, 0xc0
	s_cmpk_lt_u32 s0, 0xc0
	s_cbranch_scc1 .LBB0_10
	s_cmpk_gt_i32 s58, 0x17f
	s_mov_b64 s[0:1], -1
	s_cbranch_scc0 .LBB0_105
	s_cmpk_gt_u32 s58, 0xd63
	s_cbranch_scc0 .LBB0_70
	s_cmpk_lt_u32 s58, 0xde4
	s_cbranch_scc1 .LBB0_63
	s_waitcnt lgkmcnt(0)
	s_sub_i32 s8, s58, 0xde4
	s_lshr_b32 s9, s8, 6
	s_and_b32 s8, s8, 63
	s_lshl_b32 s8, s8, 11
	v_readlane_b32 s6, v242, 3
	v_readlane_b32 s7, v242, 4
	s_bitcmp1_b32 s9, 0
	s_cselect_b64 s[0:1], s[86:87], s[84:85]
	s_cselect_b64 s[4:5], s[90:91], s[88:89]
	s_cmp_lt_u32 s9, 2
	s_cselect_b64 s[4:5], s[0:1], s[4:5]
	s_lshl_b32 s0, s9, 18
	s_add_u32 s0, s0, 0x2ff4000
	s_add_u32 s6, s6, s0
	s_addc_u32 s7, s7, 0
	v_add_u32_e32 v2, s8, v137
	v_and_b32_e32 v3, 0xffff8000, v2
	s_bitcmp1_b32 s9, 0
	s_cbranch_scc1 .Lp0c_vt
	v_and_b32_e32 v80, 0x3fc0, v2
	v_lshl_or_b32 v3, v80, 1, v3
	v_bfe_u32 v80, v2, 14, 1
	v_lshl_or_b32 v3, v80, 6, v3
	v_and_or_b32 v3, v2, 63, v3
	v_lshlrev_b32_e32 v3, 2, v3
	global_load_dword v4, v3, s[4:5]
	v_add_u32_e32 v3, 0x800, v3
	global_load_dword v5, v3, s[4:5]
	v_add_u32_e32 v3, 0x800, v3
	global_load_dword v6, v3, s[4:5]
	v_add_u32_e32 v3, 0x800, v3
	global_load_dword v7, v3, s[4:5]
	v_add_u32_e32 v3, 0x800, v3
	global_load_dword v8, v3, s[4:5]
	v_add_u32_e32 v3, 0x800, v3
	global_load_dword v9, v3, s[4:5]
	v_add_u32_e32 v3, 0x800, v3
	global_load_dword v10, v3, s[4:5]
	v_add_u32_e32 v3, 0x800, v3
	global_load_dword v11, v3, s[4:5]
	s_branch .Lp0c_st

.Lwcm1_done:
	s_waitcnt vmcnt(0) lgkmcnt(0)
	s_barrier
	v_readlane_b32 s99, v242, 0
	s_nop 0
	s_sub_u32 s100, s99, 0x100
	s_waitcnt vmcnt(0) lgkmcnt(0)
	s_barrier
	v_readlane_b32 s0, v242, 42
	v_readlane_b32 s1, v242, 43
	v_readlane_b32 s12, v242, 3
	v_readlane_b32 s13, v242, 4
	s_sub_u32 s0, s0, 0x118
	s_subb_u32 s1, s1, 0
	s_load_dwordx4 s[20:23], s[0:1], 0x38
	s_load_dwordx4 s[24:27], s[0:1], 0x48
	v_lshlrev_b32_e32 v106, 2, v137
	v_add_u32_e32 v107, 0x1000, v106
	v_lshrrev_b32_e32 v113, 5, v137
	v_and_b32_e32 v114, 31, v137
	s_waitcnt lgkmcnt(0)
	global_load_dword v90, v106, s[22:23]
	global_load_dword v91, v106, s[22:23] offset:1024
	global_load_dword v92, v106, s[22:23] offset:2048
	global_load_dword v93, v106, s[22:23] offset:3072
	global_load_dword v94, v106, s[20:21]
	global_load_dword v95, v106, s[20:21] offset:1024
	global_load_dword v96, v106, s[20:21] offset:2048
	global_load_dword v97, v106, s[20:21] offset:3072
	global_load_dword v98, v107, s[20:21]
	global_load_dword v99, v107, s[20:21] offset:1024
	global_load_dword v100, v107, s[20:21] offset:2048
	global_load_dword v101, v107, s[20:21] offset:3072
	s_lshl_b32 s14, s100, 7
	s_add_u32 s24, s24, 0x1800000
	s_addc_u32 s25, s25, 0
	s_add_u32 s24, s24, s14
	s_addc_u32 s25, s25, 0
	v_mul_u32_u24_e32 v116, 0x300000, v113
	v_lshl_add_u32 v116, v114, 2, v116
	v_mov_b32_e32 v117, 0
	v_lshl_add_u64 v[116:117], s[24:25], 0, v[116:117]
	s_mov_b64 s[8:9], 0x6000
	v_lshlrev_b32_e32 v108, 9, v113
	s_waitcnt vmcnt(11)
	v_mul_f32_e32 v102, 0xbfb8aa3b, v90
	v_exp_f32_e32 v102, v102
	s_nop 0
	v_add_f32_e32 v102, 1.0, v102
	v_rcp_f32_e32 v102, v102
	s_nop 0
	v_mul_f32_e32 v102, v90, v102
	ds_write_b32 v106, v102
	s_waitcnt vmcnt(10)
	v_mul_f32_e32 v103, 0xbfb8aa3b, v91
	v_exp_f32_e32 v103, v103
	s_nop 0
	v_add_f32_e32 v103, 1.0, v103
	v_rcp_f32_e32 v103, v103
	s_nop 0
	v_mul_f32_e32 v103, v91, v103
	ds_write_b32 v106, v103 offset:1024
	s_waitcnt vmcnt(9)
	v_mul_f32_e32 v104, 0xbfb8aa3b, v92
	v_exp_f32_e32 v104, v104
	s_nop 0
	v_add_f32_e32 v104, 1.0, v104
	v_rcp_f32_e32 v104, v104
	s_nop 0
	v_mul_f32_e32 v104, v92, v104
	ds_write_b32 v106, v104 offset:2048
	s_waitcnt vmcnt(8)
	v_mul_f32_e32 v105, 0xbfb8aa3b, v93
	v_exp_f32_e32 v105, v105
	s_nop 0
	v_add_f32_e32 v105, 1.0, v105
	v_rcp_f32_e32 v105, v105
	s_nop 0
	v_mul_f32_e32 v105, v93, v105
	ds_write_b32 v106, v105 offset:3072
	s_waitcnt vmcnt(7)
	v_mul_f32_e32 v102, 0xbfb8aa3b, v94
	v_exp_f32_e32 v102, v102
	s_nop 0
	v_add_f32_e32 v102, 1.0, v102
	v_rcp_f32_e32 v102, v102
	s_nop 0
	v_mul_f32_e32 v102, v94, v102
	ds_write_b32 v106, v102 offset:4096
	s_waitcnt vmcnt(6)
	v_mul_f32_e32 v103, 0xbfb8aa3b, v95
	v_exp_f32_e32 v103, v103
	s_nop 0
	v_add_f32_e32 v103, 1.0, v103
	v_rcp_f32_e32 v103, v103
	s_nop 0
	v_mul_f32_e32 v103, v95, v103
	ds_write_b32 v106, v103 offset:5120
	s_waitcnt vmcnt(5)
	v_mul_f32_e32 v104, 0xbfb8aa3b, v96
	v_exp_f32_e32 v104, v104
	s_nop 0
	v_add_f32_e32 v104, 1.0, v104
	v_rcp_f32_e32 v104, v104
	s_nop 0
	v_mul_f32_e32 v104, v96, v104
	ds_write_b32 v106, v104 offset:6144
	s_waitcnt vmcnt(4)
	v_mul_f32_e32 v105, 0xbfb8aa3b, v97
	v_exp_f32_e32 v105, v105
	s_nop 0
	v_add_f32_e32 v105, 1.0, v105
	v_rcp_f32_e32 v105, v105
	s_nop 0
	v_mul_f32_e32 v105, v97, v105
	ds_write_b32 v106, v105 offset:7168
	s_waitcnt vmcnt(3)
	v_mul_f32_e32 v102, 0xbfb8aa3b, v98
	v_exp_f32_e32 v102, v102
	s_nop 0
	v_add_f32_e32 v102, 1.0, v102
	v_rcp_f32_e32 v102, v102
	s_nop 0
	v_mul_f32_e32 v102, v98, v102
	ds_write_b32 v106, v102 offset:8192
	s_waitcnt vmcnt(2)
	v_mul_f32_e32 v103, 0xbfb8aa3b, v99
	v_exp_f32_e32 v103, v103
	s_nop 0
	v_add_f32_e32 v103, 1.0, v103
	v_rcp_f32_e32 v103, v103
	s_nop 0
	v_mul_f32_e32 v103, v99, v103
	ds_write_b32 v106, v103 offset:9216
	s_waitcnt vmcnt(1)
	v_mul_f32_e32 v104, 0xbfb8aa3b, v100
	v_exp_f32_e32 v104, v104
	s_nop 0
	v_add_f32_e32 v104, 1.0, v104
	v_rcp_f32_e32 v104, v104
	s_nop 0
	v_mul_f32_e32 v104, v100, v104
	ds_write_b32 v106, v104 offset:10240
	s_waitcnt vmcnt(0)
	v_mul_f32_e32 v105, 0xbfb8aa3b, v101
	v_exp_f32_e32 v105, v105
	s_nop 0
	v_add_f32_e32 v105, 1.0, v105
	v_rcp_f32_e32 v105, v105
	s_nop 0
	v_mul_f32_e32 v105, v101, v105
	ds_write_b32 v106, v105 offset:11264
	global_load_dword v194, v[116:117], off nt
	v_lshl_add_u64 v[116:117], v[116:117], 0, s[8:9]
	global_load_dword v195, v[116:117], off nt
	v_lshl_add_u64 v[116:117], v[116:117], 0, s[8:9]
	global_load_dword v196, v[116:117], off nt
	v_lshl_add_u64 v[116:117], v[116:117], 0, s[8:9]
	global_load_dword v197, v[116:117], off nt
	v_lshl_add_u64 v[116:117], v[116:117], 0, s[8:9]
	global_load_dword v198, v[116:117], off nt
	v_lshl_add_u64 v[116:117], v[116:117], 0, s[8:9]
	global_load_dword v199, v[116:117], off nt
	v_lshl_add_u64 v[116:117], v[116:117], 0, s[8:9]
	global_load_dword v200, v[116:117], off nt
	v_lshl_add_u64 v[116:117], v[116:117], 0, s[8:9]
	global_load_dword v201, v[116:117], off nt
	v_lshl_add_u64 v[116:117], v[116:117], 0, s[8:9]
	global_load_dword v202, v[116:117], off nt
	v_lshl_add_u64 v[116:117], v[116:117], 0, s[8:9]
	global_load_dword v203, v[116:117], off nt
	v_lshl_add_u64 v[116:117], v[116:117], 0, s[8:9]
	global_load_dword v204, v[116:117], off nt
	v_lshl_add_u64 v[116:117], v[116:117], 0, s[8:9]
	global_load_dword v205, v[116:117], off nt
	v_lshl_add_u64 v[116:117], v[116:117], 0, s[8:9]
	global_load_dword v206, v[116:117], off nt
	v_lshl_add_u64 v[116:117], v[116:117], 0, s[8:9]
	global_load_dword v207, v[116:117], off nt
	v_lshl_add_u64 v[116:117], v[116:117], 0, s[8:9]
	global_load_dword v208, v[116:117], off nt
	v_lshl_add_u64 v[116:117], v[116:117], 0, s[8:9]
	global_load_dword v209, v[116:117], off nt
	v_lshl_add_u64 v[116:117], v[116:117], 0, s[8:9]
	global_load_dword v210, v[116:117], off nt
	v_lshl_add_u64 v[116:117], v[116:117], 0, s[8:9]
	global_load_dword v211, v[116:117], off nt
	v_lshl_add_u64 v[116:117], v[116:117], 0, s[8:9]
	global_load_dword v212, v[116:117], off nt
	v_lshl_add_u64 v[116:117], v[116:117], 0, s[8:9]
	global_load_dword v213, v[116:117], off nt
	v_lshl_add_u64 v[116:117], v[116:117], 0, s[8:9]
	global_load_dword v214, v[116:117], off nt
	v_lshl_add_u64 v[116:117], v[116:117], 0, s[8:9]
	global_load_dword v215, v[116:117], off nt
	v_lshl_add_u64 v[116:117], v[116:117], 0, s[8:9]
	global_load_dword v216, v[116:117], off nt
	v_lshl_add_u64 v[116:117], v[116:117], 0, s[8:9]
	global_load_dword v217, v[116:117], off nt
	v_lshl_add_u64 v[116:117], v[116:117], 0, s[8:9]
	global_load_dword v218, v[116:117], off nt
	v_lshl_add_u64 v[116:117], v[116:117], 0, s[8:9]
	global_load_dword v219, v[116:117], off nt
	v_lshl_add_u64 v[116:117], v[116:117], 0, s[8:9]
	global_load_dword v220, v[116:117], off nt
	v_lshl_add_u64 v[116:117], v[116:117], 0, s[8:9]
	global_load_dword v221, v[116:117], off nt
	v_lshl_add_u64 v[116:117], v[116:117], 0, s[8:9]
	global_load_dword v222, v[116:117], off nt
	v_lshl_add_u64 v[116:117], v[116:117], 0, s[8:9]
	global_load_dword v223, v[116:117], off nt
	v_lshl_add_u64 v[116:117], v[116:117], 0, s[8:9]
	global_load_dword v224, v[116:117], off nt
	v_lshl_add_u64 v[116:117], v[116:117], 0, s[8:9]
	global_load_dword v225, v[116:117], off nt
	v_lshl_add_u64 v[116:117], v[116:117], 0, s[8:9]
	v_mov_b32_e32 v110, 0
	v_mov_b32_e32 v111, 0
	v_mov_b32_e32 v112, 0
	s_waitcnt lgkmcnt(0)
	s_barrier
	ds_read_b128 v[146:149], v108 offset:0
	ds_read_b128 v[150:153], v108 offset:16
	ds_read_b128 v[154:157], v108 offset:32
	ds_read_b128 v[158:161], v108 offset:48
	ds_read_b128 v[162:165], v108 offset:4096
	ds_read_b128 v[166:169], v108 offset:4112
	ds_read_b128 v[170:173], v108 offset:4128
	ds_read_b128 v[174:177], v108 offset:4144
	ds_read_b128 v[178:181], v108 offset:8192
	ds_read_b128 v[182:185], v108 offset:8208
	ds_read_b128 v[186:189], v108 offset:8224
	ds_read_b128 v[190:193], v108 offset:8240
	s_waitcnt lgkmcnt(0)
	s_waitcnt vmcnt(31)
	v_fmac_f32_e32 v110, v194, v146
	v_fmac_f32_e32 v111, v194, v162
	v_fmac_f32_e32 v112, v194, v178
	global_load_dword v194, v[116:117], off nt
	v_lshl_add_u64 v[116:117], v[116:117], 0, s[8:9]
	s_waitcnt vmcnt(31)
	v_fmac_f32_e32 v110, v195, v147
	v_fmac_f32_e32 v111, v195, v163
	v_fmac_f32_e32 v112, v195, v179
	global_load_dword v195, v[116:117], off nt
	v_lshl_add_u64 v[116:117], v[116:117], 0, s[8:9]
	s_waitcnt vmcnt(31)
	v_fmac_f32_e32 v110, v196, v148
	v_fmac_f32_e32 v111, v196, v164
	v_fmac_f32_e32 v112, v196, v180
	global_load_dword v196, v[116:117], off nt
	v_lshl_add_u64 v[116:117], v[116:117], 0, s[8:9]
	s_waitcnt vmcnt(31)
	v_fmac_f32_e32 v110, v197, v149
	v_fmac_f32_e32 v111, v197, v165
	v_fmac_f32_e32 v112, v197, v181
	global_load_dword v197, v[116:117], off nt
	v_lshl_add_u64 v[116:117], v[116:117], 0, s[8:9]
	s_waitcnt vmcnt(31)
	v_fmac_f32_e32 v110, v198, v150
	v_fmac_f32_e32 v111, v198, v166
	v_fmac_f32_e32 v112, v198, v182
	global_load_dword v198, v[116:117], off nt
	v_lshl_add_u64 v[116:117], v[116:117], 0, s[8:9]
	s_waitcnt vmcnt(31)
	v_fmac_f32_e32 v110, v199, v151
	v_fmac_f32_e32 v111, v199, v167
	v_fmac_f32_e32 v112, v199, v183
	global_load_dword v199, v[116:117], off nt
	v_lshl_add_u64 v[116:117], v[116:117], 0, s[8:9]
	s_waitcnt vmcnt(31)
	v_fmac_f32_e32 v110, v200, v152
	v_fmac_f32_e32 v111, v200, v168
	v_fmac_f32_e32 v112, v200, v184
	global_load_dword v200, v[116:117], off nt
	v_lshl_add_u64 v[116:117], v[116:117], 0, s[8:9]
	s_waitcnt vmcnt(31)
	v_fmac_f32_e32 v110, v201, v153
	v_fmac_f32_e32 v111, v201, v169
	v_fmac_f32_e32 v112, v201, v185
	global_load_dword v201, v[116:117], off nt
	v_lshl_add_u64 v[116:117], v[116:117], 0, s[8:9]
	s_waitcnt vmcnt(31)
	v_fmac_f32_e32 v110, v202, v154
	v_fmac_f32_e32 v111, v202, v170
	v_fmac_f32_e32 v112, v202, v186
	global_load_dword v202, v[116:117], off nt
	v_lshl_add_u64 v[116:117], v[116:117], 0, s[8:9]
	s_waitcnt vmcnt(31)
	v_fmac_f32_e32 v110, v203, v155
	v_fmac_f32_e32 v111, v203, v171
	v_fmac_f32_e32 v112, v203, v187
	global_load_dword v203, v[116:117], off nt
	v_lshl_add_u64 v[116:117], v[116:117], 0, s[8:9]
	s_waitcnt vmcnt(31)
	v_fmac_f32_e32 v110, v204, v156
	v_fmac_f32_e32 v111, v204, v172
	v_fmac_f32_e32 v112, v204, v188
	global_load_dword v204, v[116:117], off nt
	v_lshl_add_u64 v[116:117], v[116:117], 0, s[8:9]
	s_waitcnt vmcnt(31)
	v_fmac_f32_e32 v110, v205, v157
	v_fmac_f32_e32 v111, v205, v173
	v_fmac_f32_e32 v112, v205, v189
	global_load_dword v205, v[116:117], off nt
	v_lshl_add_u64 v[116:117], v[116:117], 0, s[8:9]
	s_waitcnt vmcnt(31)
	v_fmac_f32_e32 v110, v206, v158
	v_fmac_f32_e32 v111, v206, v174
	v_fmac_f32_e32 v112, v206, v190
	global_load_dword v206, v[116:117], off nt
	v_lshl_add_u64 v[116:117], v[116:117], 0, s[8:9]
	s_waitcnt vmcnt(31)
	v_fmac_f32_e32 v110, v207, v159
	v_fmac_f32_e32 v111, v207, v175
	v_fmac_f32_e32 v112, v207, v191
	global_load_dword v207, v[116:117], off nt
	v_lshl_add_u64 v[116:117], v[116:117], 0, s[8:9]
	s_waitcnt vmcnt(31)
	v_fmac_f32_e32 v110, v208, v160
	v_fmac_f32_e32 v111, v208, v176
	v_fmac_f32_e32 v112, v208, v192
	global_load_dword v208, v[116:117], off nt
	v_lshl_add_u64 v[116:117], v[116:117], 0, s[8:9]
	s_waitcnt vmcnt(31)
	v_fmac_f32_e32 v110, v209, v161
	v_fmac_f32_e32 v111, v209, v177
	v_fmac_f32_e32 v112, v209, v193
	global_load_dword v209, v[116:117], off nt
	v_lshl_add_u64 v[116:117], v[116:117], 0, s[8:9]
	ds_read_b128 v[146:149], v108 offset:64
	ds_read_b128 v[150:153], v108 offset:80
	ds_read_b128 v[154:157], v108 offset:96
	ds_read_b128 v[158:161], v108 offset:112
	ds_read_b128 v[162:165], v108 offset:4160
	ds_read_b128 v[166:169], v108 offset:4176
	ds_read_b128 v[170:173], v108 offset:4192
	ds_read_b128 v[174:177], v108 offset:4208
	ds_read_b128 v[178:181], v108 offset:8256
	ds_read_b128 v[182:185], v108 offset:8272
	ds_read_b128 v[186:189], v108 offset:8288
	ds_read_b128 v[190:193], v108 offset:8304
	s_waitcnt lgkmcnt(0)
	s_waitcnt vmcnt(31)
	v_fmac_f32_e32 v110, v210, v146
	v_fmac_f32_e32 v111, v210, v162
	v_fmac_f32_e32 v112, v210, v178
	global_load_dword v210, v[116:117], off nt
	v_lshl_add_u64 v[116:117], v[116:117], 0, s[8:9]
	s_waitcnt vmcnt(31)
	v_fmac_f32_e32 v110, v211, v147
	v_fmac_f32_e32 v111, v211, v163
	v_fmac_f32_e32 v112, v211, v179
	global_load_dword v211, v[116:117], off nt
	v_lshl_add_u64 v[116:117], v[116:117], 0, s[8:9]
	s_waitcnt vmcnt(31)
	v_fmac_f32_e32 v110, v212, v148
	v_fmac_f32_e32 v111, v212, v164
	v_fmac_f32_e32 v112, v212, v180
	global_load_dword v212, v[116:117], off nt
	v_lshl_add_u64 v[116:117], v[116:117], 0, s[8:9]
	s_waitcnt vmcnt(31)
	v_fmac_f32_e32 v110, v213, v149
	v_fmac_f32_e32 v111, v213, v165
	v_fmac_f32_e32 v112, v213, v181
	global_load_dword v213, v[116:117], off nt
	v_lshl_add_u64 v[116:117], v[116:117], 0, s[8:9]
	s_waitcnt vmcnt(31)
	v_fmac_f32_e32 v110, v214, v150
	v_fmac_f32_e32 v111, v214, v166
	v_fmac_f32_e32 v112, v214, v182
	global_load_dword v214, v[116:117], off nt
	v_lshl_add_u64 v[116:117], v[116:117], 0, s[8:9]
	s_waitcnt vmcnt(31)
	v_fmac_f32_e32 v110, v215, v151
	v_fmac_f32_e32 v111, v215, v167
	v_fmac_f32_e32 v112, v215, v183
	global_load_dword v215, v[116:117], off nt
	v_lshl_add_u64 v[116:117], v[116:117], 0, s[8:9]
	s_waitcnt vmcnt(31)
	v_fmac_f32_e32 v110, v216, v152
	v_fmac_f32_e32 v111, v216, v168
	v_fmac_f32_e32 v112, v216, v184
	global_load_dword v216, v[116:117], off nt
	v_lshl_add_u64 v[116:117], v[116:117], 0, s[8:9]
	s_waitcnt vmcnt(31)
	v_fmac_f32_e32 v110, v217, v153
	v_fmac_f32_e32 v111, v217, v169
	v_fmac_f32_e32 v112, v217, v185
	global_load_dword v217, v[116:117], off nt
	v_lshl_add_u64 v[116:117], v[116:117], 0, s[8:9]
	s_waitcnt vmcnt(31)
	v_fmac_f32_e32 v110, v218, v154
	v_fmac_f32_e32 v111, v218, v170
	v_fmac_f32_e32 v112, v218, v186
	global_load_dword v218, v[116:117], off nt
	v_lshl_add_u64 v[116:117], v[116:117], 0, s[8:9]
	s_waitcnt vmcnt(31)
	v_fmac_f32_e32 v110, v219, v155
	v_fmac_f32_e32 v111, v219, v171
	v_fmac_f32_e32 v112, v219, v187
	global_load_dword v219, v[116:117], off nt
	v_lshl_add_u64 v[116:117], v[116:117], 0, s[8:9]
	s_waitcnt vmcnt(31)
	v_fmac_f32_e32 v110, v220, v156
	v_fmac_f32_e32 v111, v220, v172
	v_fmac_f32_e32 v112, v220, v188
	global_load_dword v220, v[116:117], off nt
	v_lshl_add_u64 v[116:117], v[116:117], 0, s[8:9]
	s_waitcnt vmcnt(31)
	v_fmac_f32_e32 v110, v221, v157
	v_fmac_f32_e32 v111, v221, v173
	v_fmac_f32_e32 v112, v221, v189
	global_load_dword v221, v[116:117], off nt
	v_lshl_add_u64 v[116:117], v[116:117], 0, s[8:9]
	s_waitcnt vmcnt(31)
	v_fmac_f32_e32 v110, v222, v158
	v_fmac_f32_e32 v111, v222, v174
	v_fmac_f32_e32 v112, v222, v190
	global_load_dword v222, v[116:117], off nt
	v_lshl_add_u64 v[116:117], v[116:117], 0, s[8:9]
	s_waitcnt vmcnt(31)
	v_fmac_f32_e32 v110, v223, v159
	v_fmac_f32_e32 v111, v223, v175
	v_fmac_f32_e32 v112, v223, v191
	global_load_dword v223, v[116:117], off nt
	v_lshl_add_u64 v[116:117], v[116:117], 0, s[8:9]
	s_waitcnt vmcnt(31)
	v_fmac_f32_e32 v110, v224, v160
	v_fmac_f32_e32 v111, v224, v176
	v_fmac_f32_e32 v112, v224, v192
	global_load_dword v224, v[116:117], off nt
	v_lshl_add_u64 v[116:117], v[116:117], 0, s[8:9]
	s_waitcnt vmcnt(31)
	v_fmac_f32_e32 v110, v225, v161
	v_fmac_f32_e32 v111, v225, v177
	v_fmac_f32_e32 v112, v225, v193
	global_load_dword v225, v[116:117], off nt
	v_lshl_add_u64 v[116:117], v[116:117], 0, s[8:9]
	ds_read_b128 v[146:149], v108 offset:128
	ds_read_b128 v[150:153], v108 offset:144
	ds_read_b128 v[154:157], v108 offset:160
	ds_read_b128 v[158:161], v108 offset:176
	ds_read_b128 v[162:165], v108 offset:4224
	ds_read_b128 v[166:169], v108 offset:4240
	ds_read_b128 v[170:173], v108 offset:4256
	ds_read_b128 v[174:177], v108 offset:4272
	ds_read_b128 v[178:181], v108 offset:8320
	ds_read_b128 v[182:185], v108 offset:8336
	ds_read_b128 v[186:189], v108 offset:8352
	ds_read_b128 v[190:193], v108 offset:8368
	s_waitcnt lgkmcnt(0)
	s_waitcnt vmcnt(31)
	v_fmac_f32_e32 v110, v194, v146
	v_fmac_f32_e32 v111, v194, v162
	v_fmac_f32_e32 v112, v194, v178
	global_load_dword v194, v[116:117], off nt
	v_lshl_add_u64 v[116:117], v[116:117], 0, s[8:9]
	s_waitcnt vmcnt(31)
	v_fmac_f32_e32 v110, v195, v147
	v_fmac_f32_e32 v111, v195, v163
	v_fmac_f32_e32 v112, v195, v179
	global_load_dword v195, v[116:117], off nt
	v_lshl_add_u64 v[116:117], v[116:117], 0, s[8:9]
	s_waitcnt vmcnt(31)
	v_fmac_f32_e32 v110, v196, v148
	v_fmac_f32_e32 v111, v196, v164
	v_fmac_f32_e32 v112, v196, v180
	global_load_dword v196, v[116:117], off nt
	v_lshl_add_u64 v[116:117], v[116:117], 0, s[8:9]
	s_waitcnt vmcnt(31)
	v_fmac_f32_e32 v110, v197, v149
	v_fmac_f32_e32 v111, v197, v165
	v_fmac_f32_e32 v112, v197, v181
	global_load_dword v197, v[116:117], off nt
	v_lshl_add_u64 v[116:117], v[116:117], 0, s[8:9]
	s_waitcnt vmcnt(31)
	v_fmac_f32_e32 v110, v198, v150
	v_fmac_f32_e32 v111, v198, v166
	v_fmac_f32_e32 v112, v198, v182
	global_load_dword v198, v[116:117], off nt
	v_lshl_add_u64 v[116:117], v[116:117], 0, s[8:9]
	s_waitcnt vmcnt(31)
	v_fmac_f32_e32 v110, v199, v151
	v_fmac_f32_e32 v111, v199, v167
	v_fmac_f32_e32 v112, v199, v183
	global_load_dword v199, v[116:117], off nt
	v_lshl_add_u64 v[116:117], v[116:117], 0, s[8:9]
	s_waitcnt vmcnt(31)
	v_fmac_f32_e32 v110, v200, v152
	v_fmac_f32_e32 v111, v200, v168
	v_fmac_f32_e32 v112, v200, v184
	global_load_dword v200, v[116:117], off nt
	v_lshl_add_u64 v[116:117], v[116:117], 0, s[8:9]
	s_waitcnt vmcnt(31)
	v_fmac_f32_e32 v110, v201, v153
	v_fmac_f32_e32 v111, v201, v169
	v_fmac_f32_e32 v112, v201, v185
	global_load_dword v201, v[116:117], off nt
	v_lshl_add_u64 v[116:117], v[116:117], 0, s[8:9]
	s_waitcnt vmcnt(31)
	v_fmac_f32_e32 v110, v202, v154
	v_fmac_f32_e32 v111, v202, v170
	v_fmac_f32_e32 v112, v202, v186
	global_load_dword v202, v[116:117], off nt
	v_lshl_add_u64 v[116:117], v[116:117], 0, s[8:9]
	s_waitcnt vmcnt(31)
	v_fmac_f32_e32 v110, v203, v155
	v_fmac_f32_e32 v111, v203, v171
	v_fmac_f32_e32 v112, v203, v187
	global_load_dword v203, v[116:117], off nt
	v_lshl_add_u64 v[116:117], v[116:117], 0, s[8:9]
	s_waitcnt vmcnt(31)
	v_fmac_f32_e32 v110, v204, v156
	v_fmac_f32_e32 v111, v204, v172
	v_fmac_f32_e32 v112, v204, v188
	global_load_dword v204, v[116:117], off nt
	v_lshl_add_u64 v[116:117], v[116:117], 0, s[8:9]
	s_waitcnt vmcnt(31)
	v_fmac_f32_e32 v110, v205, v157
	v_fmac_f32_e32 v111, v205, v173
	v_fmac_f32_e32 v112, v205, v189
	global_load_dword v205, v[116:117], off nt
	v_lshl_add_u64 v[116:117], v[116:117], 0, s[8:9]
	s_waitcnt vmcnt(31)
	v_fmac_f32_e32 v110, v206, v158
	v_fmac_f32_e32 v111, v206, v174
	v_fmac_f32_e32 v112, v206, v190
	global_load_dword v206, v[116:117], off nt
	v_lshl_add_u64 v[116:117], v[116:117], 0, s[8:9]
	s_waitcnt vmcnt(31)
	v_fmac_f32_e32 v110, v207, v159
	v_fmac_f32_e32 v111, v207, v175
	v_fmac_f32_e32 v112, v207, v191
	global_load_dword v207, v[116:117], off nt
	v_lshl_add_u64 v[116:117], v[116:117], 0, s[8:9]
	s_waitcnt vmcnt(31)
	v_fmac_f32_e32 v110, v208, v160
	v_fmac_f32_e32 v111, v208, v176
	v_fmac_f32_e32 v112, v208, v192
	global_load_dword v208, v[116:117], off nt
	v_lshl_add_u64 v[116:117], v[116:117], 0, s[8:9]
	s_waitcnt vmcnt(31)
	v_fmac_f32_e32 v110, v209, v161
	v_fmac_f32_e32 v111, v209, v177
	v_fmac_f32_e32 v112, v209, v193
	global_load_dword v209, v[116:117], off nt
	v_lshl_add_u64 v[116:117], v[116:117], 0, s[8:9]
	ds_read_b128 v[146:149], v108 offset:192
	ds_read_b128 v[150:153], v108 offset:208
	ds_read_b128 v[154:157], v108 offset:224
	ds_read_b128 v[158:161], v108 offset:240
	ds_read_b128 v[162:165], v108 offset:4288
	ds_read_b128 v[166:169], v108 offset:4304
	ds_read_b128 v[170:173], v108 offset:4320
	ds_read_b128 v[174:177], v108 offset:4336
	ds_read_b128 v[178:181], v108 offset:8384
	ds_read_b128 v[182:185], v108 offset:8400
	ds_read_b128 v[186:189], v108 offset:8416
	ds_read_b128 v[190:193], v108 offset:8432
	s_waitcnt lgkmcnt(0)
	s_waitcnt vmcnt(31)
	v_fmac_f32_e32 v110, v210, v146
	v_fmac_f32_e32 v111, v210, v162
	v_fmac_f32_e32 v112, v210, v178
	global_load_dword v210, v[116:117], off nt
	v_lshl_add_u64 v[116:117], v[116:117], 0, s[8:9]
	s_waitcnt vmcnt(31)
	v_fmac_f32_e32 v110, v211, v147
	v_fmac_f32_e32 v111, v211, v163
	v_fmac_f32_e32 v112, v211, v179
	global_load_dword v211, v[116:117], off nt
	v_lshl_add_u64 v[116:117], v[116:117], 0, s[8:9]
	s_waitcnt vmcnt(31)
	v_fmac_f32_e32 v110, v212, v148
	v_fmac_f32_e32 v111, v212, v164
	v_fmac_f32_e32 v112, v212, v180
	global_load_dword v212, v[116:117], off nt
	v_lshl_add_u64 v[116:117], v[116:117], 0, s[8:9]
	s_waitcnt vmcnt(31)
	v_fmac_f32_e32 v110, v213, v149
	v_fmac_f32_e32 v111, v213, v165
	v_fmac_f32_e32 v112, v213, v181
	global_load_dword v213, v[116:117], off nt
	v_lshl_add_u64 v[116:117], v[116:117], 0, s[8:9]
	s_waitcnt vmcnt(31)
	v_fmac_f32_e32 v110, v214, v150
	v_fmac_f32_e32 v111, v214, v166
	v_fmac_f32_e32 v112, v214, v182
	global_load_dword v214, v[116:117], off nt
	v_lshl_add_u64 v[116:117], v[116:117], 0, s[8:9]
	s_waitcnt vmcnt(31)
	v_fmac_f32_e32 v110, v215, v151
	v_fmac_f32_e32 v111, v215, v167
	v_fmac_f32_e32 v112, v215, v183
	global_load_dword v215, v[116:117], off nt
	v_lshl_add_u64 v[116:117], v[116:117], 0, s[8:9]
	s_waitcnt vmcnt(31)
	v_fmac_f32_e32 v110, v216, v152
	v_fmac_f32_e32 v111, v216, v168
	v_fmac_f32_e32 v112, v216, v184
	global_load_dword v216, v[116:117], off nt
	v_lshl_add_u64 v[116:117], v[116:117], 0, s[8:9]
	s_waitcnt vmcnt(31)
	v_fmac_f32_e32 v110, v217, v153
	v_fmac_f32_e32 v111, v217, v169
	v_fmac_f32_e32 v112, v217, v185
	global_load_dword v217, v[116:117], off nt
	v_lshl_add_u64 v[116:117], v[116:117], 0, s[8:9]
	s_waitcnt vmcnt(31)
	v_fmac_f32_e32 v110, v218, v154
	v_fmac_f32_e32 v111, v218, v170
	v_fmac_f32_e32 v112, v218, v186
	global_load_dword v218, v[116:117], off nt
	v_lshl_add_u64 v[116:117], v[116:117], 0, s[8:9]
	s_waitcnt vmcnt(31)
	v_fmac_f32_e32 v110, v219, v155
	v_fmac_f32_e32 v111, v219, v171
	v_fmac_f32_e32 v112, v219, v187
	global_load_dword v219, v[116:117], off nt
	v_lshl_add_u64 v[116:117], v[116:117], 0, s[8:9]
	s_waitcnt vmcnt(31)
	v_fmac_f32_e32 v110, v220, v156
	v_fmac_f32_e32 v111, v220, v172
	v_fmac_f32_e32 v112, v220, v188
	global_load_dword v220, v[116:117], off nt
	v_lshl_add_u64 v[116:117], v[116:117], 0, s[8:9]
	s_waitcnt vmcnt(31)
	v_fmac_f32_e32 v110, v221, v157
	v_fmac_f32_e32 v111, v221, v173
	v_fmac_f32_e32 v112, v221, v189
	global_load_dword v221, v[116:117], off nt
	v_lshl_add_u64 v[116:117], v[116:117], 0, s[8:9]
	s_waitcnt vmcnt(31)
	v_fmac_f32_e32 v110, v222, v158
	v_fmac_f32_e32 v111, v222, v174
	v_fmac_f32_e32 v112, v222, v190
	global_load_dword v222, v[116:117], off nt
	v_lshl_add_u64 v[116:117], v[116:117], 0, s[8:9]
	s_waitcnt vmcnt(31)
	v_fmac_f32_e32 v110, v223, v159
	v_fmac_f32_e32 v111, v223, v175
	v_fmac_f32_e32 v112, v223, v191
	global_load_dword v223, v[116:117], off nt
	v_lshl_add_u64 v[116:117], v[116:117], 0, s[8:9]
	s_waitcnt vmcnt(31)
	v_fmac_f32_e32 v110, v224, v160
	v_fmac_f32_e32 v111, v224, v176
	v_fmac_f32_e32 v112, v224, v192
	global_load_dword v224, v[116:117], off nt
	v_lshl_add_u64 v[116:117], v[116:117], 0, s[8:9]
	s_waitcnt vmcnt(31)
	v_fmac_f32_e32 v110, v225, v161
	v_fmac_f32_e32 v111, v225, v177
	v_fmac_f32_e32 v112, v225, v193
	global_load_dword v225, v[116:117], off nt
	v_lshl_add_u64 v[116:117], v[116:117], 0, s[8:9]
	ds_read_b128 v[146:149], v108 offset:256
	ds_read_b128 v[150:153], v108 offset:272
	ds_read_b128 v[154:157], v108 offset:288
	ds_read_b128 v[158:161], v108 offset:304
	ds_read_b128 v[162:165], v108 offset:4352
	ds_read_b128 v[166:169], v108 offset:4368
	ds_read_b128 v[170:173], v108 offset:4384
	ds_read_b128 v[174:177], v108 offset:4400
	ds_read_b128 v[178:181], v108 offset:8448
	ds_read_b128 v[182:185], v108 offset:8464
	ds_read_b128 v[186:189], v108 offset:8480
	ds_read_b128 v[190:193], v108 offset:8496
	s_waitcnt lgkmcnt(0)
	s_waitcnt vmcnt(31)
	v_fmac_f32_e32 v110, v194, v146
	v_fmac_f32_e32 v111, v194, v162
	v_fmac_f32_e32 v112, v194, v178
	global_load_dword v194, v[116:117], off nt
	v_lshl_add_u64 v[116:117], v[116:117], 0, s[8:9]
	s_waitcnt vmcnt(31)
	v_fmac_f32_e32 v110, v195, v147
	v_fmac_f32_e32 v111, v195, v163
	v_fmac_f32_e32 v112, v195, v179
	global_load_dword v195, v[116:117], off nt
	v_lshl_add_u64 v[116:117], v[116:117], 0, s[8:9]
	s_waitcnt vmcnt(31)
	v_fmac_f32_e32 v110, v196, v148
	v_fmac_f32_e32 v111, v196, v164
	v_fmac_f32_e32 v112, v196, v180
	global_load_dword v196, v[116:117], off nt
	v_lshl_add_u64 v[116:117], v[116:117], 0, s[8:9]
	s_waitcnt vmcnt(31)
	v_fmac_f32_e32 v110, v197, v149
	v_fmac_f32_e32 v111, v197, v165
	v_fmac_f32_e32 v112, v197, v181
	global_load_dword v197, v[116:117], off nt
	v_lshl_add_u64 v[116:117], v[116:117], 0, s[8:9]
	s_waitcnt vmcnt(31)
	v_fmac_f32_e32 v110, v198, v150
	v_fmac_f32_e32 v111, v198, v166
	v_fmac_f32_e32 v112, v198, v182
	global_load_dword v198, v[116:117], off nt
	v_lshl_add_u64 v[116:117], v[116:117], 0, s[8:9]
	s_waitcnt vmcnt(31)
	v_fmac_f32_e32 v110, v199, v151
	v_fmac_f32_e32 v111, v199, v167
	v_fmac_f32_e32 v112, v199, v183
	global_load_dword v199, v[116:117], off nt
	v_lshl_add_u64 v[116:117], v[116:117], 0, s[8:9]
	s_waitcnt vmcnt(31)
	v_fmac_f32_e32 v110, v200, v152
	v_fmac_f32_e32 v111, v200, v168
	v_fmac_f32_e32 v112, v200, v184
	global_load_dword v200, v[116:117], off nt
	v_lshl_add_u64 v[116:117], v[116:117], 0, s[8:9]
	s_waitcnt vmcnt(31)
	v_fmac_f32_e32 v110, v201, v153
	v_fmac_f32_e32 v111, v201, v169
	v_fmac_f32_e32 v112, v201, v185
	global_load_dword v201, v[116:117], off nt
	v_lshl_add_u64 v[116:117], v[116:117], 0, s[8:9]
	s_waitcnt vmcnt(31)
	v_fmac_f32_e32 v110, v202, v154
	v_fmac_f32_e32 v111, v202, v170
	v_fmac_f32_e32 v112, v202, v186
	global_load_dword v202, v[116:117], off nt
	v_lshl_add_u64 v[116:117], v[116:117], 0, s[8:9]
	s_waitcnt vmcnt(31)
	v_fmac_f32_e32 v110, v203, v155
	v_fmac_f32_e32 v111, v203, v171
	v_fmac_f32_e32 v112, v203, v187
	global_load_dword v203, v[116:117], off nt
	v_lshl_add_u64 v[116:117], v[116:117], 0, s[8:9]
	s_waitcnt vmcnt(31)
	v_fmac_f32_e32 v110, v204, v156
	v_fmac_f32_e32 v111, v204, v172
	v_fmac_f32_e32 v112, v204, v188
	global_load_dword v204, v[116:117], off nt
	v_lshl_add_u64 v[116:117], v[116:117], 0, s[8:9]
	s_waitcnt vmcnt(31)
	v_fmac_f32_e32 v110, v205, v157
	v_fmac_f32_e32 v111, v205, v173
	v_fmac_f32_e32 v112, v205, v189
	global_load_dword v205, v[116:117], off nt
	v_lshl_add_u64 v[116:117], v[116:117], 0, s[8:9]
	s_waitcnt vmcnt(31)
	v_fmac_f32_e32 v110, v206, v158
	v_fmac_f32_e32 v111, v206, v174
	v_fmac_f32_e32 v112, v206, v190
	global_load_dword v206, v[116:117], off nt
	v_lshl_add_u64 v[116:117], v[116:117], 0, s[8:9]
	s_waitcnt vmcnt(31)
	v_fmac_f32_e32 v110, v207, v159
	v_fmac_f32_e32 v111, v207, v175
	v_fmac_f32_e32 v112, v207, v191
	global_load_dword v207, v[116:117], off nt
	v_lshl_add_u64 v[116:117], v[116:117], 0, s[8:9]
	s_waitcnt vmcnt(31)
	v_fmac_f32_e32 v110, v208, v160
	v_fmac_f32_e32 v111, v208, v176
	v_fmac_f32_e32 v112, v208, v192
	global_load_dword v208, v[116:117], off nt
	v_lshl_add_u64 v[116:117], v[116:117], 0, s[8:9]
	s_waitcnt vmcnt(31)
	v_fmac_f32_e32 v110, v209, v161
	v_fmac_f32_e32 v111, v209, v177
	v_fmac_f32_e32 v112, v209, v193
	global_load_dword v209, v[116:117], off nt
	v_lshl_add_u64 v[116:117], v[116:117], 0, s[8:9]
	ds_read_b128 v[146:149], v108 offset:320
	ds_read_b128 v[150:153], v108 offset:336
	ds_read_b128 v[154:157], v108 offset:352
	ds_read_b128 v[158:161], v108 offset:368
	ds_read_b128 v[162:165], v108 offset:4416
	ds_read_b128 v[166:169], v108 offset:4432
	ds_read_b128 v[170:173], v108 offset:4448
	ds_read_b128 v[174:177], v108 offset:4464
	ds_read_b128 v[178:181], v108 offset:8512
	ds_read_b128 v[182:185], v108 offset:8528
	ds_read_b128 v[186:189], v108 offset:8544
	ds_read_b128 v[190:193], v108 offset:8560
	s_waitcnt lgkmcnt(0)
	s_waitcnt vmcnt(31)
	v_fmac_f32_e32 v110, v210, v146
	v_fmac_f32_e32 v111, v210, v162
	v_fmac_f32_e32 v112, v210, v178
	global_load_dword v210, v[116:117], off nt
	v_lshl_add_u64 v[116:117], v[116:117], 0, s[8:9]
	s_waitcnt vmcnt(31)
	v_fmac_f32_e32 v110, v211, v147
	v_fmac_f32_e32 v111, v211, v163
	v_fmac_f32_e32 v112, v211, v179
	global_load_dword v211, v[116:117], off nt
	v_lshl_add_u64 v[116:117], v[116:117], 0, s[8:9]
	s_waitcnt vmcnt(31)
	v_fmac_f32_e32 v110, v212, v148
	v_fmac_f32_e32 v111, v212, v164
	v_fmac_f32_e32 v112, v212, v180
	global_load_dword v212, v[116:117], off nt
	v_lshl_add_u64 v[116:117], v[116:117], 0, s[8:9]
	s_waitcnt vmcnt(31)
	v_fmac_f32_e32 v110, v213, v149
	v_fmac_f32_e32 v111, v213, v165
	v_fmac_f32_e32 v112, v213, v181
	global_load_dword v213, v[116:117], off nt
	v_lshl_add_u64 v[116:117], v[116:117], 0, s[8:9]
	s_waitcnt vmcnt(31)
	v_fmac_f32_e32 v110, v214, v150
	v_fmac_f32_e32 v111, v214, v166
	v_fmac_f32_e32 v112, v214, v182
	global_load_dword v214, v[116:117], off nt
	v_lshl_add_u64 v[116:117], v[116:117], 0, s[8:9]
	s_waitcnt vmcnt(31)
	v_fmac_f32_e32 v110, v215, v151
	v_fmac_f32_e32 v111, v215, v167
	v_fmac_f32_e32 v112, v215, v183
	global_load_dword v215, v[116:117], off nt
	v_lshl_add_u64 v[116:117], v[116:117], 0, s[8:9]
	s_waitcnt vmcnt(31)
	v_fmac_f32_e32 v110, v216, v152
	v_fmac_f32_e32 v111, v216, v168
	v_fmac_f32_e32 v112, v216, v184
	global_load_dword v216, v[116:117], off nt
	v_lshl_add_u64 v[116:117], v[116:117], 0, s[8:9]
	s_waitcnt vmcnt(31)
	v_fmac_f32_e32 v110, v217, v153
	v_fmac_f32_e32 v111, v217, v169
	v_fmac_f32_e32 v112, v217, v185
	global_load_dword v217, v[116:117], off nt
	v_lshl_add_u64 v[116:117], v[116:117], 0, s[8:9]
	s_waitcnt vmcnt(31)
	v_fmac_f32_e32 v110, v218, v154
	v_fmac_f32_e32 v111, v218, v170
	v_fmac_f32_e32 v112, v218, v186
	global_load_dword v218, v[116:117], off nt
	v_lshl_add_u64 v[116:117], v[116:117], 0, s[8:9]
	s_waitcnt vmcnt(31)
	v_fmac_f32_e32 v110, v219, v155
	v_fmac_f32_e32 v111, v219, v171
	v_fmac_f32_e32 v112, v219, v187
	global_load_dword v219, v[116:117], off nt
	v_lshl_add_u64 v[116:117], v[116:117], 0, s[8:9]
	s_waitcnt vmcnt(31)
	v_fmac_f32_e32 v110, v220, v156
	v_fmac_f32_e32 v111, v220, v172
	v_fmac_f32_e32 v112, v220, v188
	global_load_dword v220, v[116:117], off nt
	v_lshl_add_u64 v[116:117], v[116:117], 0, s[8:9]
	s_waitcnt vmcnt(31)
	v_fmac_f32_e32 v110, v221, v157
	v_fmac_f32_e32 v111, v221, v173
	v_fmac_f32_e32 v112, v221, v189
	global_load_dword v221, v[116:117], off nt
	v_lshl_add_u64 v[116:117], v[116:117], 0, s[8:9]
	s_waitcnt vmcnt(31)
	v_fmac_f32_e32 v110, v222, v158
	v_fmac_f32_e32 v111, v222, v174
	v_fmac_f32_e32 v112, v222, v190
	global_load_dword v222, v[116:117], off nt
	v_lshl_add_u64 v[116:117], v[116:117], 0, s[8:9]
	s_waitcnt vmcnt(31)
	v_fmac_f32_e32 v110, v223, v159
	v_fmac_f32_e32 v111, v223, v175
	v_fmac_f32_e32 v112, v223, v191
	global_load_dword v223, v[116:117], off nt
	v_lshl_add_u64 v[116:117], v[116:117], 0, s[8:9]
	s_waitcnt vmcnt(31)
	v_fmac_f32_e32 v110, v224, v160
	v_fmac_f32_e32 v111, v224, v176
	v_fmac_f32_e32 v112, v224, v192
	global_load_dword v224, v[116:117], off nt
	v_lshl_add_u64 v[116:117], v[116:117], 0, s[8:9]
	s_waitcnt vmcnt(31)
	v_fmac_f32_e32 v110, v225, v161
	v_fmac_f32_e32 v111, v225, v177
	v_fmac_f32_e32 v112, v225, v193
	global_load_dword v225, v[116:117], off nt
	v_lshl_add_u64 v[116:117], v[116:117], 0, s[8:9]
	ds_read_b128 v[146:149], v108 offset:384
	ds_read_b128 v[150:153], v108 offset:400
	ds_read_b128 v[154:157], v108 offset:416
	ds_read_b128 v[158:161], v108 offset:432
	ds_read_b128 v[162:165], v108 offset:4480
	ds_read_b128 v[166:169], v108 offset:4496
	ds_read_b128 v[170:173], v108 offset:4512
	ds_read_b128 v[174:177], v108 offset:4528
	ds_read_b128 v[178:181], v108 offset:8576
	ds_read_b128 v[182:185], v108 offset:8592
	ds_read_b128 v[186:189], v108 offset:8608
	ds_read_b128 v[190:193], v108 offset:8624
	s_waitcnt lgkmcnt(0)
	s_waitcnt vmcnt(31)
	v_fmac_f32_e32 v110, v194, v146
	v_fmac_f32_e32 v111, v194, v162
	v_fmac_f32_e32 v112, v194, v178
	s_waitcnt vmcnt(30)
	v_fmac_f32_e32 v110, v195, v147
	v_fmac_f32_e32 v111, v195, v163
	v_fmac_f32_e32 v112, v195, v179
	s_waitcnt vmcnt(29)
	v_fmac_f32_e32 v110, v196, v148
	v_fmac_f32_e32 v111, v196, v164
	v_fmac_f32_e32 v112, v196, v180
	s_waitcnt vmcnt(28)
	v_fmac_f32_e32 v110, v197, v149
	v_fmac_f32_e32 v111, v197, v165
	v_fmac_f32_e32 v112, v197, v181
	s_waitcnt vmcnt(27)
	v_fmac_f32_e32 v110, v198, v150
	v_fmac_f32_e32 v111, v198, v166
	v_fmac_f32_e32 v112, v198, v182
	s_waitcnt vmcnt(26)
	v_fmac_f32_e32 v110, v199, v151
	v_fmac_f32_e32 v111, v199, v167
	v_fmac_f32_e32 v112, v199, v183
	s_waitcnt vmcnt(25)
	v_fmac_f32_e32 v110, v200, v152
	v_fmac_f32_e32 v111, v200, v168
	v_fmac_f32_e32 v112, v200, v184
	s_waitcnt vmcnt(24)
	v_fmac_f32_e32 v110, v201, v153
	v_fmac_f32_e32 v111, v201, v169
	v_fmac_f32_e32 v112, v201, v185
	s_waitcnt vmcnt(23)
	v_fmac_f32_e32 v110, v202, v154
	v_fmac_f32_e32 v111, v202, v170
	v_fmac_f32_e32 v112, v202, v186
	s_waitcnt vmcnt(22)
	v_fmac_f32_e32 v110, v203, v155
	v_fmac_f32_e32 v111, v203, v171
	v_fmac_f32_e32 v112, v203, v187
	s_waitcnt vmcnt(21)
	v_fmac_f32_e32 v110, v204, v156
	v_fmac_f32_e32 v111, v204, v172
	v_fmac_f32_e32 v112, v204, v188
	s_waitcnt vmcnt(20)
	v_fmac_f32_e32 v110, v205, v157
	v_fmac_f32_e32 v111, v205, v173
	v_fmac_f32_e32 v112, v205, v189
	s_waitcnt vmcnt(19)
	v_fmac_f32_e32 v110, v206, v158
	v_fmac_f32_e32 v111, v206, v174
	v_fmac_f32_e32 v112, v206, v190
	s_waitcnt vmcnt(18)
	v_fmac_f32_e32 v110, v207, v159
	v_fmac_f32_e32 v111, v207, v175
	v_fmac_f32_e32 v112, v207, v191
	s_waitcnt vmcnt(17)
	v_fmac_f32_e32 v110, v208, v160
	v_fmac_f32_e32 v111, v208, v176
	v_fmac_f32_e32 v112, v208, v192
	s_waitcnt vmcnt(16)
	v_fmac_f32_e32 v110, v209, v161
	v_fmac_f32_e32 v111, v209, v177
	v_fmac_f32_e32 v112, v209, v193
	ds_read_b128 v[146:149], v108 offset:448
	ds_read_b128 v[150:153], v108 offset:464
	ds_read_b128 v[154:157], v108 offset:480
	ds_read_b128 v[158:161], v108 offset:496
	ds_read_b128 v[162:165], v108 offset:4544
	ds_read_b128 v[166:169], v108 offset:4560
	ds_read_b128 v[170:173], v108 offset:4576
	ds_read_b128 v[174:177], v108 offset:4592
	ds_read_b128 v[178:181], v108 offset:8640
	ds_read_b128 v[182:185], v108 offset:8656
	ds_read_b128 v[186:189], v108 offset:8672
	ds_read_b128 v[190:193], v108 offset:8688
	s_waitcnt lgkmcnt(0)
	s_waitcnt vmcnt(15)
	v_fmac_f32_e32 v110, v210, v146
	v_fmac_f32_e32 v111, v210, v162
	v_fmac_f32_e32 v112, v210, v178
	s_waitcnt vmcnt(14)
	v_fmac_f32_e32 v110, v211, v147
	v_fmac_f32_e32 v111, v211, v163
	v_fmac_f32_e32 v112, v211, v179
	s_waitcnt vmcnt(13)
	v_fmac_f32_e32 v110, v212, v148
	v_fmac_f32_e32 v111, v212, v164
	v_fmac_f32_e32 v112, v212, v180
	s_waitcnt vmcnt(12)
	v_fmac_f32_e32 v110, v213, v149
	v_fmac_f32_e32 v111, v213, v165
	v_fmac_f32_e32 v112, v213, v181
	s_waitcnt vmcnt(11)
	v_fmac_f32_e32 v110, v214, v150
	v_fmac_f32_e32 v111, v214, v166
	v_fmac_f32_e32 v112, v214, v182
	s_waitcnt vmcnt(10)
	v_fmac_f32_e32 v110, v215, v151
	v_fmac_f32_e32 v111, v215, v167
	v_fmac_f32_e32 v112, v215, v183
	s_waitcnt vmcnt(9)
	v_fmac_f32_e32 v110, v216, v152
	v_fmac_f32_e32 v111, v216, v168
	v_fmac_f32_e32 v112, v216, v184
	s_waitcnt vmcnt(8)
	v_fmac_f32_e32 v110, v217, v153
	v_fmac_f32_e32 v111, v217, v169
	v_fmac_f32_e32 v112, v217, v185
	s_waitcnt vmcnt(7)
	v_fmac_f32_e32 v110, v218, v154
	v_fmac_f32_e32 v111, v218, v170
	v_fmac_f32_e32 v112, v218, v186
	s_waitcnt vmcnt(6)
	v_fmac_f32_e32 v110, v219, v155
	v_fmac_f32_e32 v111, v219, v171
	v_fmac_f32_e32 v112, v219, v187
	s_waitcnt vmcnt(5)
	v_fmac_f32_e32 v110, v220, v156
	v_fmac_f32_e32 v111, v220, v172
	v_fmac_f32_e32 v112, v220, v188
	s_waitcnt vmcnt(4)
	v_fmac_f32_e32 v110, v221, v157
	v_fmac_f32_e32 v111, v221, v173
	v_fmac_f32_e32 v112, v221, v189
	s_waitcnt vmcnt(3)
	v_fmac_f32_e32 v110, v222, v158
	v_fmac_f32_e32 v111, v222, v174
	v_fmac_f32_e32 v112, v222, v190
	s_waitcnt vmcnt(2)
	v_fmac_f32_e32 v110, v223, v159
	v_fmac_f32_e32 v111, v223, v175
	v_fmac_f32_e32 v112, v223, v191
	s_waitcnt vmcnt(1)
	v_fmac_f32_e32 v110, v224, v160
	v_fmac_f32_e32 v111, v224, v176
	v_fmac_f32_e32 v112, v224, v192
	s_waitcnt vmcnt(0)
	v_fmac_f32_e32 v110, v225, v161
	v_fmac_f32_e32 v111, v225, v177
	v_fmac_f32_e32 v112, v225, v193
	v_mul_u32_u24_e32 v109, 0x180, v113
	v_lshl_add_u32 v109, v114, 2, v109
	ds_write_b32 v109, v110 offset:12288
	ds_write_b32 v109, v111 offset:12416
	ds_write_b32 v109, v112 offset:12544
	s_waitcnt lgkmcnt(0)
	s_barrier
	v_cmp_gt_u32_e32 vcc, 0x60, v137
	s_and_saveexec_b64 s[14:15], vcc
	s_cbranch_execz .Lgvm0_skip
	s_lshl_b32 s16, s100, 7
	s_add_u32 s16, s16, 0x6000
	v_lshl_add_u32 v102, v114, 2, s16
	global_load_dword v103, v102, s[26:27]
	v_lshlrev_b32_e32 v104, 7, v113
	v_lshl_add_u32 v104, v114, 2, v104
	ds_read_b32 v146, v104 offset:12288
	ds_read_b32 v147, v104 offset:12672
	ds_read_b32 v148, v104 offset:13056
	ds_read_b32 v149, v104 offset:13440
	ds_read_b32 v150, v104 offset:13824
	ds_read_b32 v151, v104 offset:14208
	ds_read_b32 v152, v104 offset:14592
	ds_read_b32 v153, v104 offset:14976
	v_mul_u32_u24_e32 v105, 0x6000, v113
	v_add_u32_e32 v105, v105, v102
	s_add_u32 s12, s12, 0x2f9c000
	s_addc_u32 s13, s13, 0
	s_waitcnt vmcnt(0) lgkmcnt(0)
	v_add_f32_e32 v103, v103, v146
	v_add_f32_e32 v103, v103, v147
	v_add_f32_e32 v103, v103, v148
	v_add_f32_e32 v103, v103, v149
	v_add_f32_e32 v103, v103, v150
	v_add_f32_e32 v103, v103, v151
	v_add_f32_e32 v103, v103, v152
	v_add_f32_e32 v103, v103, v153
	global_store_dword v105, v103, s[12:13]
.Lgvm0_skip:
	s_or_b64 exec, exec, s[14:15]
	s_waitcnt vmcnt(0) lgkmcnt(0)
	s_barrier
	s_add_u32 s100, s100, 96
	s_waitcnt vmcnt(0) lgkmcnt(0)
	s_barrier
	v_readlane_b32 s0, v242, 42
	v_readlane_b32 s1, v242, 43
	v_readlane_b32 s12, v242, 3
	v_readlane_b32 s13, v242, 4
	s_sub_u32 s0, s0, 0x118
	s_subb_u32 s1, s1, 0
	s_load_dwordx4 s[20:23], s[0:1], 0x38
	s_load_dwordx4 s[24:27], s[0:1], 0x48
	v_lshlrev_b32_e32 v106, 2, v137
	v_add_u32_e32 v107, 0x1000, v106
	v_lshrrev_b32_e32 v113, 5, v137
	v_and_b32_e32 v114, 31, v137
	s_waitcnt lgkmcnt(0)
	global_load_dword v90, v106, s[22:23]
	global_load_dword v91, v106, s[22:23] offset:1024
	global_load_dword v92, v106, s[22:23] offset:2048
	global_load_dword v93, v106, s[22:23] offset:3072
	global_load_dword v94, v106, s[20:21]
	global_load_dword v95, v106, s[20:21] offset:1024
	global_load_dword v96, v106, s[20:21] offset:2048
	global_load_dword v97, v106, s[20:21] offset:3072
	global_load_dword v98, v107, s[20:21]
	global_load_dword v99, v107, s[20:21] offset:1024
	global_load_dword v100, v107, s[20:21] offset:2048
	global_load_dword v101, v107, s[20:21] offset:3072
	s_lshl_b32 s14, s100, 7
	s_add_u32 s24, s24, 0x1800000
	s_addc_u32 s25, s25, 0
	s_add_u32 s24, s24, s14
	s_addc_u32 s25, s25, 0
	v_mul_u32_u24_e32 v116, 0x300000, v113
	v_lshl_add_u32 v116, v114, 2, v116
	v_mov_b32_e32 v117, 0
	v_lshl_add_u64 v[116:117], s[24:25], 0, v[116:117]
	s_mov_b64 s[8:9], 0x6000
	v_lshlrev_b32_e32 v108, 9, v113
	s_waitcnt vmcnt(11)
	v_mul_f32_e32 v102, 0xbfb8aa3b, v90
	v_exp_f32_e32 v102, v102
	s_nop 0
	v_add_f32_e32 v102, 1.0, v102
	v_rcp_f32_e32 v102, v102
	s_nop 0
	v_mul_f32_e32 v102, v90, v102
	ds_write_b32 v106, v102
	s_waitcnt vmcnt(10)
	v_mul_f32_e32 v103, 0xbfb8aa3b, v91
	v_exp_f32_e32 v103, v103
	s_nop 0
	v_add_f32_e32 v103, 1.0, v103
	v_rcp_f32_e32 v103, v103
	s_nop 0
	v_mul_f32_e32 v103, v91, v103
	ds_write_b32 v106, v103 offset:1024
	s_waitcnt vmcnt(9)
	v_mul_f32_e32 v104, 0xbfb8aa3b, v92
	v_exp_f32_e32 v104, v104
	s_nop 0
	v_add_f32_e32 v104, 1.0, v104
	v_rcp_f32_e32 v104, v104
	s_nop 0
	v_mul_f32_e32 v104, v92, v104
	ds_write_b32 v106, v104 offset:2048
	s_waitcnt vmcnt(8)
	v_mul_f32_e32 v105, 0xbfb8aa3b, v93
	v_exp_f32_e32 v105, v105
	s_nop 0
	v_add_f32_e32 v105, 1.0, v105
	v_rcp_f32_e32 v105, v105
	s_nop 0
	v_mul_f32_e32 v105, v93, v105
	ds_write_b32 v106, v105 offset:3072
	s_waitcnt vmcnt(7)
	v_mul_f32_e32 v102, 0xbfb8aa3b, v94
	v_exp_f32_e32 v102, v102
	s_nop 0
	v_add_f32_e32 v102, 1.0, v102
	v_rcp_f32_e32 v102, v102
	s_nop 0
	v_mul_f32_e32 v102, v94, v102
	ds_write_b32 v106, v102 offset:4096
	s_waitcnt vmcnt(6)
	v_mul_f32_e32 v103, 0xbfb8aa3b, v95
	v_exp_f32_e32 v103, v103
	s_nop 0
	v_add_f32_e32 v103, 1.0, v103
	v_rcp_f32_e32 v103, v103
	s_nop 0
	v_mul_f32_e32 v103, v95, v103
	ds_write_b32 v106, v103 offset:5120
	s_waitcnt vmcnt(5)
	v_mul_f32_e32 v104, 0xbfb8aa3b, v96
	v_exp_f32_e32 v104, v104
	s_nop 0
	v_add_f32_e32 v104, 1.0, v104
	v_rcp_f32_e32 v104, v104
	s_nop 0
	v_mul_f32_e32 v104, v96, v104
	ds_write_b32 v106, v104 offset:6144
	s_waitcnt vmcnt(4)
	v_mul_f32_e32 v105, 0xbfb8aa3b, v97
	v_exp_f32_e32 v105, v105
	s_nop 0
	v_add_f32_e32 v105, 1.0, v105
	v_rcp_f32_e32 v105, v105
	s_nop 0
	v_mul_f32_e32 v105, v97, v105
	ds_write_b32 v106, v105 offset:7168
	s_waitcnt vmcnt(3)
	v_mul_f32_e32 v102, 0xbfb8aa3b, v98
	v_exp_f32_e32 v102, v102
	s_nop 0
	v_add_f32_e32 v102, 1.0, v102
	v_rcp_f32_e32 v102, v102
	s_nop 0
	v_mul_f32_e32 v102, v98, v102
	ds_write_b32 v106, v102 offset:8192
	s_waitcnt vmcnt(2)
	v_mul_f32_e32 v103, 0xbfb8aa3b, v99
	v_exp_f32_e32 v103, v103
	s_nop 0
	v_add_f32_e32 v103, 1.0, v103
	v_rcp_f32_e32 v103, v103
	s_nop 0
	v_mul_f32_e32 v103, v99, v103
	ds_write_b32 v106, v103 offset:9216
	s_waitcnt vmcnt(1)
	v_mul_f32_e32 v104, 0xbfb8aa3b, v100
	v_exp_f32_e32 v104, v104
	s_nop 0
	v_add_f32_e32 v104, 1.0, v104
	v_rcp_f32_e32 v104, v104
	s_nop 0
	v_mul_f32_e32 v104, v100, v104
	ds_write_b32 v106, v104 offset:10240
	s_waitcnt vmcnt(0)
	v_mul_f32_e32 v105, 0xbfb8aa3b, v101
	v_exp_f32_e32 v105, v105
	s_nop 0
	v_add_f32_e32 v105, 1.0, v105
	v_rcp_f32_e32 v105, v105
	s_nop 0
	v_mul_f32_e32 v105, v101, v105
	ds_write_b32 v106, v105 offset:11264
	global_load_dword v194, v[116:117], off nt
	v_lshl_add_u64 v[116:117], v[116:117], 0, s[8:9]
	global_load_dword v195, v[116:117], off nt
	v_lshl_add_u64 v[116:117], v[116:117], 0, s[8:9]
	global_load_dword v196, v[116:117], off nt
	v_lshl_add_u64 v[116:117], v[116:117], 0, s[8:9]
	global_load_dword v197, v[116:117], off nt
	v_lshl_add_u64 v[116:117], v[116:117], 0, s[8:9]
	global_load_dword v198, v[116:117], off nt
	v_lshl_add_u64 v[116:117], v[116:117], 0, s[8:9]
	global_load_dword v199, v[116:117], off nt
	v_lshl_add_u64 v[116:117], v[116:117], 0, s[8:9]
	global_load_dword v200, v[116:117], off nt
	v_lshl_add_u64 v[116:117], v[116:117], 0, s[8:9]
	global_load_dword v201, v[116:117], off nt
	v_lshl_add_u64 v[116:117], v[116:117], 0, s[8:9]
	global_load_dword v202, v[116:117], off nt
	v_lshl_add_u64 v[116:117], v[116:117], 0, s[8:9]
	global_load_dword v203, v[116:117], off nt
	v_lshl_add_u64 v[116:117], v[116:117], 0, s[8:9]
	global_load_dword v204, v[116:117], off nt
	v_lshl_add_u64 v[116:117], v[116:117], 0, s[8:9]
	global_load_dword v205, v[116:117], off nt
	v_lshl_add_u64 v[116:117], v[116:117], 0, s[8:9]
	global_load_dword v206, v[116:117], off nt
	v_lshl_add_u64 v[116:117], v[116:117], 0, s[8:9]
	global_load_dword v207, v[116:117], off nt
	v_lshl_add_u64 v[116:117], v[116:117], 0, s[8:9]
	global_load_dword v208, v[116:117], off nt
	v_lshl_add_u64 v[116:117], v[116:117], 0, s[8:9]
	global_load_dword v209, v[116:117], off nt
	v_lshl_add_u64 v[116:117], v[116:117], 0, s[8:9]
	global_load_dword v210, v[116:117], off nt
	v_lshl_add_u64 v[116:117], v[116:117], 0, s[8:9]
	global_load_dword v211, v[116:117], off nt
	v_lshl_add_u64 v[116:117], v[116:117], 0, s[8:9]
	global_load_dword v212, v[116:117], off nt
	v_lshl_add_u64 v[116:117], v[116:117], 0, s[8:9]
	global_load_dword v213, v[116:117], off nt
	v_lshl_add_u64 v[116:117], v[116:117], 0, s[8:9]
	global_load_dword v214, v[116:117], off nt
	v_lshl_add_u64 v[116:117], v[116:117], 0, s[8:9]
	global_load_dword v215, v[116:117], off nt
	v_lshl_add_u64 v[116:117], v[116:117], 0, s[8:9]
	global_load_dword v216, v[116:117], off nt
	v_lshl_add_u64 v[116:117], v[116:117], 0, s[8:9]
	global_load_dword v217, v[116:117], off nt
	v_lshl_add_u64 v[116:117], v[116:117], 0, s[8:9]
	global_load_dword v218, v[116:117], off nt
	v_lshl_add_u64 v[116:117], v[116:117], 0, s[8:9]
	global_load_dword v219, v[116:117], off nt
	v_lshl_add_u64 v[116:117], v[116:117], 0, s[8:9]
	global_load_dword v220, v[116:117], off nt
	v_lshl_add_u64 v[116:117], v[116:117], 0, s[8:9]
	global_load_dword v221, v[116:117], off nt
	v_lshl_add_u64 v[116:117], v[116:117], 0, s[8:9]
	global_load_dword v222, v[116:117], off nt
	v_lshl_add_u64 v[116:117], v[116:117], 0, s[8:9]
	global_load_dword v223, v[116:117], off nt
	v_lshl_add_u64 v[116:117], v[116:117], 0, s[8:9]
	global_load_dword v224, v[116:117], off nt
	v_lshl_add_u64 v[116:117], v[116:117], 0, s[8:9]
	global_load_dword v225, v[116:117], off nt
	v_lshl_add_u64 v[116:117], v[116:117], 0, s[8:9]
	v_mov_b32_e32 v110, 0
	v_mov_b32_e32 v111, 0
	v_mov_b32_e32 v112, 0
	s_waitcnt lgkmcnt(0)
	s_barrier
	ds_read_b128 v[146:149], v108 offset:0
	ds_read_b128 v[150:153], v108 offset:16
	ds_read_b128 v[154:157], v108 offset:32
	ds_read_b128 v[158:161], v108 offset:48
	ds_read_b128 v[162:165], v108 offset:4096
	ds_read_b128 v[166:169], v108 offset:4112
	ds_read_b128 v[170:173], v108 offset:4128
	ds_read_b128 v[174:177], v108 offset:4144
	ds_read_b128 v[178:181], v108 offset:8192
	ds_read_b128 v[182:185], v108 offset:8208
	ds_read_b128 v[186:189], v108 offset:8224
	ds_read_b128 v[190:193], v108 offset:8240
	s_waitcnt lgkmcnt(0)
	s_waitcnt vmcnt(31)
	v_fmac_f32_e32 v110, v194, v146
	v_fmac_f32_e32 v111, v194, v162
	v_fmac_f32_e32 v112, v194, v178
	global_load_dword v194, v[116:117], off nt
	v_lshl_add_u64 v[116:117], v[116:117], 0, s[8:9]
	s_waitcnt vmcnt(31)
	v_fmac_f32_e32 v110, v195, v147
	v_fmac_f32_e32 v111, v195, v163
	v_fmac_f32_e32 v112, v195, v179
	global_load_dword v195, v[116:117], off nt
	v_lshl_add_u64 v[116:117], v[116:117], 0, s[8:9]
	s_waitcnt vmcnt(31)
	v_fmac_f32_e32 v110, v196, v148
	v_fmac_f32_e32 v111, v196, v164
	v_fmac_f32_e32 v112, v196, v180
	global_load_dword v196, v[116:117], off nt
	v_lshl_add_u64 v[116:117], v[116:117], 0, s[8:9]
	s_waitcnt vmcnt(31)
	v_fmac_f32_e32 v110, v197, v149
	v_fmac_f32_e32 v111, v197, v165
	v_fmac_f32_e32 v112, v197, v181
	global_load_dword v197, v[116:117], off nt
	v_lshl_add_u64 v[116:117], v[116:117], 0, s[8:9]
	s_waitcnt vmcnt(31)
	v_fmac_f32_e32 v110, v198, v150
	v_fmac_f32_e32 v111, v198, v166
	v_fmac_f32_e32 v112, v198, v182
	global_load_dword v198, v[116:117], off nt
	v_lshl_add_u64 v[116:117], v[116:117], 0, s[8:9]
	s_waitcnt vmcnt(31)
	v_fmac_f32_e32 v110, v199, v151
	v_fmac_f32_e32 v111, v199, v167
	v_fmac_f32_e32 v112, v199, v183
	global_load_dword v199, v[116:117], off nt
	v_lshl_add_u64 v[116:117], v[116:117], 0, s[8:9]
	s_waitcnt vmcnt(31)
	v_fmac_f32_e32 v110, v200, v152
	v_fmac_f32_e32 v111, v200, v168
	v_fmac_f32_e32 v112, v200, v184
	global_load_dword v200, v[116:117], off nt
	v_lshl_add_u64 v[116:117], v[116:117], 0, s[8:9]
	s_waitcnt vmcnt(31)
	v_fmac_f32_e32 v110, v201, v153
	v_fmac_f32_e32 v111, v201, v169
	v_fmac_f32_e32 v112, v201, v185
	global_load_dword v201, v[116:117], off nt
	v_lshl_add_u64 v[116:117], v[116:117], 0, s[8:9]
	s_waitcnt vmcnt(31)
	v_fmac_f32_e32 v110, v202, v154
	v_fmac_f32_e32 v111, v202, v170
	v_fmac_f32_e32 v112, v202, v186
	global_load_dword v202, v[116:117], off nt
	v_lshl_add_u64 v[116:117], v[116:117], 0, s[8:9]
	s_waitcnt vmcnt(31)
	v_fmac_f32_e32 v110, v203, v155
	v_fmac_f32_e32 v111, v203, v171
	v_fmac_f32_e32 v112, v203, v187
	global_load_dword v203, v[116:117], off nt
	v_lshl_add_u64 v[116:117], v[116:117], 0, s[8:9]
	s_waitcnt vmcnt(31)
	v_fmac_f32_e32 v110, v204, v156
	v_fmac_f32_e32 v111, v204, v172
	v_fmac_f32_e32 v112, v204, v188
	global_load_dword v204, v[116:117], off nt
	v_lshl_add_u64 v[116:117], v[116:117], 0, s[8:9]
	s_waitcnt vmcnt(31)
	v_fmac_f32_e32 v110, v205, v157
	v_fmac_f32_e32 v111, v205, v173
	v_fmac_f32_e32 v112, v205, v189
	global_load_dword v205, v[116:117], off nt
	v_lshl_add_u64 v[116:117], v[116:117], 0, s[8:9]
	s_waitcnt vmcnt(31)
	v_fmac_f32_e32 v110, v206, v158
	v_fmac_f32_e32 v111, v206, v174
	v_fmac_f32_e32 v112, v206, v190
	global_load_dword v206, v[116:117], off nt
	v_lshl_add_u64 v[116:117], v[116:117], 0, s[8:9]
	s_waitcnt vmcnt(31)
	v_fmac_f32_e32 v110, v207, v159
	v_fmac_f32_e32 v111, v207, v175
	v_fmac_f32_e32 v112, v207, v191
	global_load_dword v207, v[116:117], off nt
	v_lshl_add_u64 v[116:117], v[116:117], 0, s[8:9]
	s_waitcnt vmcnt(31)
	v_fmac_f32_e32 v110, v208, v160
	v_fmac_f32_e32 v111, v208, v176
	v_fmac_f32_e32 v112, v208, v192
	global_load_dword v208, v[116:117], off nt
	v_lshl_add_u64 v[116:117], v[116:117], 0, s[8:9]
	s_waitcnt vmcnt(31)
	v_fmac_f32_e32 v110, v209, v161
	v_fmac_f32_e32 v111, v209, v177
	v_fmac_f32_e32 v112, v209, v193
	global_load_dword v209, v[116:117], off nt
	v_lshl_add_u64 v[116:117], v[116:117], 0, s[8:9]
	ds_read_b128 v[146:149], v108 offset:64
	ds_read_b128 v[150:153], v108 offset:80
	ds_read_b128 v[154:157], v108 offset:96
	ds_read_b128 v[158:161], v108 offset:112
	ds_read_b128 v[162:165], v108 offset:4160
	ds_read_b128 v[166:169], v108 offset:4176
	ds_read_b128 v[170:173], v108 offset:4192
	ds_read_b128 v[174:177], v108 offset:4208
	ds_read_b128 v[178:181], v108 offset:8256
	ds_read_b128 v[182:185], v108 offset:8272
	ds_read_b128 v[186:189], v108 offset:8288
	ds_read_b128 v[190:193], v108 offset:8304
	s_waitcnt lgkmcnt(0)
	s_waitcnt vmcnt(31)
	v_fmac_f32_e32 v110, v210, v146
	v_fmac_f32_e32 v111, v210, v162
	v_fmac_f32_e32 v112, v210, v178
	global_load_dword v210, v[116:117], off nt
	v_lshl_add_u64 v[116:117], v[116:117], 0, s[8:9]
	s_waitcnt vmcnt(31)
	v_fmac_f32_e32 v110, v211, v147
	v_fmac_f32_e32 v111, v211, v163
	v_fmac_f32_e32 v112, v211, v179
	global_load_dword v211, v[116:117], off nt
	v_lshl_add_u64 v[116:117], v[116:117], 0, s[8:9]
	s_waitcnt vmcnt(31)
	v_fmac_f32_e32 v110, v212, v148
	v_fmac_f32_e32 v111, v212, v164
	v_fmac_f32_e32 v112, v212, v180
	global_load_dword v212, v[116:117], off nt
	v_lshl_add_u64 v[116:117], v[116:117], 0, s[8:9]
	s_waitcnt vmcnt(31)
	v_fmac_f32_e32 v110, v213, v149
	v_fmac_f32_e32 v111, v213, v165
	v_fmac_f32_e32 v112, v213, v181
	global_load_dword v213, v[116:117], off nt
	v_lshl_add_u64 v[116:117], v[116:117], 0, s[8:9]
	s_waitcnt vmcnt(31)
	v_fmac_f32_e32 v110, v214, v150
	v_fmac_f32_e32 v111, v214, v166
	v_fmac_f32_e32 v112, v214, v182
	global_load_dword v214, v[116:117], off nt
	v_lshl_add_u64 v[116:117], v[116:117], 0, s[8:9]
	s_waitcnt vmcnt(31)
	v_fmac_f32_e32 v110, v215, v151
	v_fmac_f32_e32 v111, v215, v167
	v_fmac_f32_e32 v112, v215, v183
	global_load_dword v215, v[116:117], off nt
	v_lshl_add_u64 v[116:117], v[116:117], 0, s[8:9]
	s_waitcnt vmcnt(31)
	v_fmac_f32_e32 v110, v216, v152
	v_fmac_f32_e32 v111, v216, v168
	v_fmac_f32_e32 v112, v216, v184
	global_load_dword v216, v[116:117], off nt
	v_lshl_add_u64 v[116:117], v[116:117], 0, s[8:9]
	s_waitcnt vmcnt(31)
	v_fmac_f32_e32 v110, v217, v153
	v_fmac_f32_e32 v111, v217, v169
	v_fmac_f32_e32 v112, v217, v185
	global_load_dword v217, v[116:117], off nt
	v_lshl_add_u64 v[116:117], v[116:117], 0, s[8:9]
	s_waitcnt vmcnt(31)
	v_fmac_f32_e32 v110, v218, v154
	v_fmac_f32_e32 v111, v218, v170
	v_fmac_f32_e32 v112, v218, v186
	global_load_dword v218, v[116:117], off nt
	v_lshl_add_u64 v[116:117], v[116:117], 0, s[8:9]
	s_waitcnt vmcnt(31)
	v_fmac_f32_e32 v110, v219, v155
	v_fmac_f32_e32 v111, v219, v171
	v_fmac_f32_e32 v112, v219, v187
	global_load_dword v219, v[116:117], off nt
	v_lshl_add_u64 v[116:117], v[116:117], 0, s[8:9]
	s_waitcnt vmcnt(31)
	v_fmac_f32_e32 v110, v220, v156
	v_fmac_f32_e32 v111, v220, v172
	v_fmac_f32_e32 v112, v220, v188
	global_load_dword v220, v[116:117], off nt
	v_lshl_add_u64 v[116:117], v[116:117], 0, s[8:9]
	s_waitcnt vmcnt(31)
	v_fmac_f32_e32 v110, v221, v157
	v_fmac_f32_e32 v111, v221, v173
	v_fmac_f32_e32 v112, v221, v189
	global_load_dword v221, v[116:117], off nt
	v_lshl_add_u64 v[116:117], v[116:117], 0, s[8:9]
	s_waitcnt vmcnt(31)
	v_fmac_f32_e32 v110, v222, v158
	v_fmac_f32_e32 v111, v222, v174
	v_fmac_f32_e32 v112, v222, v190
	global_load_dword v222, v[116:117], off nt
	v_lshl_add_u64 v[116:117], v[116:117], 0, s[8:9]
	s_waitcnt vmcnt(31)
	v_fmac_f32_e32 v110, v223, v159
	v_fmac_f32_e32 v111, v223, v175
	v_fmac_f32_e32 v112, v223, v191
	global_load_dword v223, v[116:117], off nt
	v_lshl_add_u64 v[116:117], v[116:117], 0, s[8:9]
	s_waitcnt vmcnt(31)
	v_fmac_f32_e32 v110, v224, v160
	v_fmac_f32_e32 v111, v224, v176
	v_fmac_f32_e32 v112, v224, v192
	global_load_dword v224, v[116:117], off nt
	v_lshl_add_u64 v[116:117], v[116:117], 0, s[8:9]
	s_waitcnt vmcnt(31)
	v_fmac_f32_e32 v110, v225, v161
	v_fmac_f32_e32 v111, v225, v177
	v_fmac_f32_e32 v112, v225, v193
	global_load_dword v225, v[116:117], off nt
	v_lshl_add_u64 v[116:117], v[116:117], 0, s[8:9]
	ds_read_b128 v[146:149], v108 offset:128
	ds_read_b128 v[150:153], v108 offset:144
	ds_read_b128 v[154:157], v108 offset:160
	ds_read_b128 v[158:161], v108 offset:176
	ds_read_b128 v[162:165], v108 offset:4224
	ds_read_b128 v[166:169], v108 offset:4240
	ds_read_b128 v[170:173], v108 offset:4256
	ds_read_b128 v[174:177], v108 offset:4272
	ds_read_b128 v[178:181], v108 offset:8320
	ds_read_b128 v[182:185], v108 offset:8336
	ds_read_b128 v[186:189], v108 offset:8352
	ds_read_b128 v[190:193], v108 offset:8368
	s_waitcnt lgkmcnt(0)
	s_waitcnt vmcnt(31)
	v_fmac_f32_e32 v110, v194, v146
	v_fmac_f32_e32 v111, v194, v162
	v_fmac_f32_e32 v112, v194, v178
	global_load_dword v194, v[116:117], off nt
	v_lshl_add_u64 v[116:117], v[116:117], 0, s[8:9]
	s_waitcnt vmcnt(31)
	v_fmac_f32_e32 v110, v195, v147
	v_fmac_f32_e32 v111, v195, v163
	v_fmac_f32_e32 v112, v195, v179
	global_load_dword v195, v[116:117], off nt
	v_lshl_add_u64 v[116:117], v[116:117], 0, s[8:9]
	s_waitcnt vmcnt(31)
	v_fmac_f32_e32 v110, v196, v148
	v_fmac_f32_e32 v111, v196, v164
	v_fmac_f32_e32 v112, v196, v180
	global_load_dword v196, v[116:117], off nt
	v_lshl_add_u64 v[116:117], v[116:117], 0, s[8:9]
	s_waitcnt vmcnt(31)
	v_fmac_f32_e32 v110, v197, v149
	v_fmac_f32_e32 v111, v197, v165
	v_fmac_f32_e32 v112, v197, v181
	global_load_dword v197, v[116:117], off nt
	v_lshl_add_u64 v[116:117], v[116:117], 0, s[8:9]
	s_waitcnt vmcnt(31)
	v_fmac_f32_e32 v110, v198, v150
	v_fmac_f32_e32 v111, v198, v166
	v_fmac_f32_e32 v112, v198, v182
	global_load_dword v198, v[116:117], off nt
	v_lshl_add_u64 v[116:117], v[116:117], 0, s[8:9]
	s_waitcnt vmcnt(31)
	v_fmac_f32_e32 v110, v199, v151
	v_fmac_f32_e32 v111, v199, v167
	v_fmac_f32_e32 v112, v199, v183
	global_load_dword v199, v[116:117], off nt
	v_lshl_add_u64 v[116:117], v[116:117], 0, s[8:9]
	s_waitcnt vmcnt(31)
	v_fmac_f32_e32 v110, v200, v152
	v_fmac_f32_e32 v111, v200, v168
	v_fmac_f32_e32 v112, v200, v184
	global_load_dword v200, v[116:117], off nt
	v_lshl_add_u64 v[116:117], v[116:117], 0, s[8:9]
	s_waitcnt vmcnt(31)
	v_fmac_f32_e32 v110, v201, v153
	v_fmac_f32_e32 v111, v201, v169
	v_fmac_f32_e32 v112, v201, v185
	global_load_dword v201, v[116:117], off nt
	v_lshl_add_u64 v[116:117], v[116:117], 0, s[8:9]
	s_waitcnt vmcnt(31)
	v_fmac_f32_e32 v110, v202, v154
	v_fmac_f32_e32 v111, v202, v170
	v_fmac_f32_e32 v112, v202, v186
	global_load_dword v202, v[116:117], off nt
	v_lshl_add_u64 v[116:117], v[116:117], 0, s[8:9]
	s_waitcnt vmcnt(31)
	v_fmac_f32_e32 v110, v203, v155
	v_fmac_f32_e32 v111, v203, v171
	v_fmac_f32_e32 v112, v203, v187
	global_load_dword v203, v[116:117], off nt
	v_lshl_add_u64 v[116:117], v[116:117], 0, s[8:9]
	s_waitcnt vmcnt(31)
	v_fmac_f32_e32 v110, v204, v156
	v_fmac_f32_e32 v111, v204, v172
	v_fmac_f32_e32 v112, v204, v188
	global_load_dword v204, v[116:117], off nt
	v_lshl_add_u64 v[116:117], v[116:117], 0, s[8:9]
	s_waitcnt vmcnt(31)
	v_fmac_f32_e32 v110, v205, v157
	v_fmac_f32_e32 v111, v205, v173
	v_fmac_f32_e32 v112, v205, v189
	global_load_dword v205, v[116:117], off nt
	v_lshl_add_u64 v[116:117], v[116:117], 0, s[8:9]
	s_waitcnt vmcnt(31)
	v_fmac_f32_e32 v110, v206, v158
	v_fmac_f32_e32 v111, v206, v174
	v_fmac_f32_e32 v112, v206, v190
	global_load_dword v206, v[116:117], off nt
	v_lshl_add_u64 v[116:117], v[116:117], 0, s[8:9]
	s_waitcnt vmcnt(31)
	v_fmac_f32_e32 v110, v207, v159
	v_fmac_f32_e32 v111, v207, v175
	v_fmac_f32_e32 v112, v207, v191
	global_load_dword v207, v[116:117], off nt
	v_lshl_add_u64 v[116:117], v[116:117], 0, s[8:9]
	s_waitcnt vmcnt(31)
	v_fmac_f32_e32 v110, v208, v160
	v_fmac_f32_e32 v111, v208, v176
	v_fmac_f32_e32 v112, v208, v192
	global_load_dword v208, v[116:117], off nt
	v_lshl_add_u64 v[116:117], v[116:117], 0, s[8:9]
	s_waitcnt vmcnt(31)
	v_fmac_f32_e32 v110, v209, v161
	v_fmac_f32_e32 v111, v209, v177
	v_fmac_f32_e32 v112, v209, v193
	global_load_dword v209, v[116:117], off nt
	v_lshl_add_u64 v[116:117], v[116:117], 0, s[8:9]
	ds_read_b128 v[146:149], v108 offset:192
	ds_read_b128 v[150:153], v108 offset:208
	ds_read_b128 v[154:157], v108 offset:224
	ds_read_b128 v[158:161], v108 offset:240
	ds_read_b128 v[162:165], v108 offset:4288
	ds_read_b128 v[166:169], v108 offset:4304
	ds_read_b128 v[170:173], v108 offset:4320
	ds_read_b128 v[174:177], v108 offset:4336
	ds_read_b128 v[178:181], v108 offset:8384
	ds_read_b128 v[182:185], v108 offset:8400
	ds_read_b128 v[186:189], v108 offset:8416
	ds_read_b128 v[190:193], v108 offset:8432
	s_waitcnt lgkmcnt(0)
	s_waitcnt vmcnt(31)
	v_fmac_f32_e32 v110, v210, v146
	v_fmac_f32_e32 v111, v210, v162
	v_fmac_f32_e32 v112, v210, v178
	global_load_dword v210, v[116:117], off nt
	v_lshl_add_u64 v[116:117], v[116:117], 0, s[8:9]
	s_waitcnt vmcnt(31)
	v_fmac_f32_e32 v110, v211, v147
	v_fmac_f32_e32 v111, v211, v163
	v_fmac_f32_e32 v112, v211, v179
	global_load_dword v211, v[116:117], off nt
	v_lshl_add_u64 v[116:117], v[116:117], 0, s[8:9]
	s_waitcnt vmcnt(31)
	v_fmac_f32_e32 v110, v212, v148
	v_fmac_f32_e32 v111, v212, v164
	v_fmac_f32_e32 v112, v212, v180
	global_load_dword v212, v[116:117], off nt
	v_lshl_add_u64 v[116:117], v[116:117], 0, s[8:9]
	s_waitcnt vmcnt(31)
	v_fmac_f32_e32 v110, v213, v149
	v_fmac_f32_e32 v111, v213, v165
	v_fmac_f32_e32 v112, v213, v181
	global_load_dword v213, v[116:117], off nt
	v_lshl_add_u64 v[116:117], v[116:117], 0, s[8:9]
	s_waitcnt vmcnt(31)
	v_fmac_f32_e32 v110, v214, v150
	v_fmac_f32_e32 v111, v214, v166
	v_fmac_f32_e32 v112, v214, v182
	global_load_dword v214, v[116:117], off nt
	v_lshl_add_u64 v[116:117], v[116:117], 0, s[8:9]
	s_waitcnt vmcnt(31)
	v_fmac_f32_e32 v110, v215, v151
	v_fmac_f32_e32 v111, v215, v167
	v_fmac_f32_e32 v112, v215, v183
	global_load_dword v215, v[116:117], off nt
	v_lshl_add_u64 v[116:117], v[116:117], 0, s[8:9]
	s_waitcnt vmcnt(31)
	v_fmac_f32_e32 v110, v216, v152
	v_fmac_f32_e32 v111, v216, v168
	v_fmac_f32_e32 v112, v216, v184
	global_load_dword v216, v[116:117], off nt
	v_lshl_add_u64 v[116:117], v[116:117], 0, s[8:9]
	s_waitcnt vmcnt(31)
	v_fmac_f32_e32 v110, v217, v153
	v_fmac_f32_e32 v111, v217, v169
	v_fmac_f32_e32 v112, v217, v185
	global_load_dword v217, v[116:117], off nt
	v_lshl_add_u64 v[116:117], v[116:117], 0, s[8:9]
	s_waitcnt vmcnt(31)
	v_fmac_f32_e32 v110, v218, v154
	v_fmac_f32_e32 v111, v218, v170
	v_fmac_f32_e32 v112, v218, v186
	global_load_dword v218, v[116:117], off nt
	v_lshl_add_u64 v[116:117], v[116:117], 0, s[8:9]
	s_waitcnt vmcnt(31)
	v_fmac_f32_e32 v110, v219, v155
	v_fmac_f32_e32 v111, v219, v171
	v_fmac_f32_e32 v112, v219, v187
	global_load_dword v219, v[116:117], off nt
	v_lshl_add_u64 v[116:117], v[116:117], 0, s[8:9]
	s_waitcnt vmcnt(31)
	v_fmac_f32_e32 v110, v220, v156
	v_fmac_f32_e32 v111, v220, v172
	v_fmac_f32_e32 v112, v220, v188
	global_load_dword v220, v[116:117], off nt
	v_lshl_add_u64 v[116:117], v[116:117], 0, s[8:9]
	s_waitcnt vmcnt(31)
	v_fmac_f32_e32 v110, v221, v157
	v_fmac_f32_e32 v111, v221, v173
	v_fmac_f32_e32 v112, v221, v189
	global_load_dword v221, v[116:117], off nt
	v_lshl_add_u64 v[116:117], v[116:117], 0, s[8:9]
	s_waitcnt vmcnt(31)
	v_fmac_f32_e32 v110, v222, v158
	v_fmac_f32_e32 v111, v222, v174
	v_fmac_f32_e32 v112, v222, v190
	global_load_dword v222, v[116:117], off nt
	v_lshl_add_u64 v[116:117], v[116:117], 0, s[8:9]
	s_waitcnt vmcnt(31)
	v_fmac_f32_e32 v110, v223, v159
	v_fmac_f32_e32 v111, v223, v175
	v_fmac_f32_e32 v112, v223, v191
	global_load_dword v223, v[116:117], off nt
	v_lshl_add_u64 v[116:117], v[116:117], 0, s[8:9]
	s_waitcnt vmcnt(31)
	v_fmac_f32_e32 v110, v224, v160
	v_fmac_f32_e32 v111, v224, v176
	v_fmac_f32_e32 v112, v224, v192
	global_load_dword v224, v[116:117], off nt
	v_lshl_add_u64 v[116:117], v[116:117], 0, s[8:9]
	s_waitcnt vmcnt(31)
	v_fmac_f32_e32 v110, v225, v161
	v_fmac_f32_e32 v111, v225, v177
	v_fmac_f32_e32 v112, v225, v193
	global_load_dword v225, v[116:117], off nt
	v_lshl_add_u64 v[116:117], v[116:117], 0, s[8:9]
	ds_read_b128 v[146:149], v108 offset:256
	ds_read_b128 v[150:153], v108 offset:272
	ds_read_b128 v[154:157], v108 offset:288
	ds_read_b128 v[158:161], v108 offset:304
	ds_read_b128 v[162:165], v108 offset:4352
	ds_read_b128 v[166:169], v108 offset:4368
	ds_read_b128 v[170:173], v108 offset:4384
	ds_read_b128 v[174:177], v108 offset:4400
	ds_read_b128 v[178:181], v108 offset:8448
	ds_read_b128 v[182:185], v108 offset:8464
	ds_read_b128 v[186:189], v108 offset:8480
	ds_read_b128 v[190:193], v108 offset:8496
	s_waitcnt lgkmcnt(0)
	s_waitcnt vmcnt(31)
	v_fmac_f32_e32 v110, v194, v146
	v_fmac_f32_e32 v111, v194, v162
	v_fmac_f32_e32 v112, v194, v178
	global_load_dword v194, v[116:117], off nt
	v_lshl_add_u64 v[116:117], v[116:117], 0, s[8:9]
	s_waitcnt vmcnt(31)
	v_fmac_f32_e32 v110, v195, v147
	v_fmac_f32_e32 v111, v195, v163
	v_fmac_f32_e32 v112, v195, v179
	global_load_dword v195, v[116:117], off nt
	v_lshl_add_u64 v[116:117], v[116:117], 0, s[8:9]
	s_waitcnt vmcnt(31)
	v_fmac_f32_e32 v110, v196, v148
	v_fmac_f32_e32 v111, v196, v164
	v_fmac_f32_e32 v112, v196, v180
	global_load_dword v196, v[116:117], off nt
	v_lshl_add_u64 v[116:117], v[116:117], 0, s[8:9]
	s_waitcnt vmcnt(31)
	v_fmac_f32_e32 v110, v197, v149
	v_fmac_f32_e32 v111, v197, v165
	v_fmac_f32_e32 v112, v197, v181
	global_load_dword v197, v[116:117], off nt
	v_lshl_add_u64 v[116:117], v[116:117], 0, s[8:9]
	s_waitcnt vmcnt(31)
	v_fmac_f32_e32 v110, v198, v150
	v_fmac_f32_e32 v111, v198, v166
	v_fmac_f32_e32 v112, v198, v182
	global_load_dword v198, v[116:117], off nt
	v_lshl_add_u64 v[116:117], v[116:117], 0, s[8:9]
	s_waitcnt vmcnt(31)
	v_fmac_f32_e32 v110, v199, v151
	v_fmac_f32_e32 v111, v199, v167
	v_fmac_f32_e32 v112, v199, v183
	global_load_dword v199, v[116:117], off nt
	v_lshl_add_u64 v[116:117], v[116:117], 0, s[8:9]
	s_waitcnt vmcnt(31)
	v_fmac_f32_e32 v110, v200, v152
	v_fmac_f32_e32 v111, v200, v168
	v_fmac_f32_e32 v112, v200, v184
	global_load_dword v200, v[116:117], off nt
	v_lshl_add_u64 v[116:117], v[116:117], 0, s[8:9]
	s_waitcnt vmcnt(31)
	v_fmac_f32_e32 v110, v201, v153
	v_fmac_f32_e32 v111, v201, v169
	v_fmac_f32_e32 v112, v201, v185
	global_load_dword v201, v[116:117], off nt
	v_lshl_add_u64 v[116:117], v[116:117], 0, s[8:9]
	s_waitcnt vmcnt(31)
	v_fmac_f32_e32 v110, v202, v154
	v_fmac_f32_e32 v111, v202, v170
	v_fmac_f32_e32 v112, v202, v186
	global_load_dword v202, v[116:117], off nt
	v_lshl_add_u64 v[116:117], v[116:117], 0, s[8:9]
	s_waitcnt vmcnt(31)
	v_fmac_f32_e32 v110, v203, v155
	v_fmac_f32_e32 v111, v203, v171
	v_fmac_f32_e32 v112, v203, v187
	global_load_dword v203, v[116:117], off nt
	v_lshl_add_u64 v[116:117], v[116:117], 0, s[8:9]
	s_waitcnt vmcnt(31)
	v_fmac_f32_e32 v110, v204, v156
	v_fmac_f32_e32 v111, v204, v172
	v_fmac_f32_e32 v112, v204, v188
	global_load_dword v204, v[116:117], off nt
	v_lshl_add_u64 v[116:117], v[116:117], 0, s[8:9]
	s_waitcnt vmcnt(31)
	v_fmac_f32_e32 v110, v205, v157
	v_fmac_f32_e32 v111, v205, v173
	v_fmac_f32_e32 v112, v205, v189
	global_load_dword v205, v[116:117], off nt
	v_lshl_add_u64 v[116:117], v[116:117], 0, s[8:9]
	s_waitcnt vmcnt(31)
	v_fmac_f32_e32 v110, v206, v158
	v_fmac_f32_e32 v111, v206, v174
	v_fmac_f32_e32 v112, v206, v190
	global_load_dword v206, v[116:117], off nt
	v_lshl_add_u64 v[116:117], v[116:117], 0, s[8:9]
	s_waitcnt vmcnt(31)
	v_fmac_f32_e32 v110, v207, v159
	v_fmac_f32_e32 v111, v207, v175
	v_fmac_f32_e32 v112, v207, v191
	global_load_dword v207, v[116:117], off nt
	v_lshl_add_u64 v[116:117], v[116:117], 0, s[8:9]
	s_waitcnt vmcnt(31)
	v_fmac_f32_e32 v110, v208, v160
	v_fmac_f32_e32 v111, v208, v176
	v_fmac_f32_e32 v112, v208, v192
	global_load_dword v208, v[116:117], off nt
	v_lshl_add_u64 v[116:117], v[116:117], 0, s[8:9]
	s_waitcnt vmcnt(31)
	v_fmac_f32_e32 v110, v209, v161
	v_fmac_f32_e32 v111, v209, v177
	v_fmac_f32_e32 v112, v209, v193
	global_load_dword v209, v[116:117], off nt
	v_lshl_add_u64 v[116:117], v[116:117], 0, s[8:9]
	ds_read_b128 v[146:149], v108 offset:320
	ds_read_b128 v[150:153], v108 offset:336
	ds_read_b128 v[154:157], v108 offset:352
	ds_read_b128 v[158:161], v108 offset:368
	ds_read_b128 v[162:165], v108 offset:4416
	ds_read_b128 v[166:169], v108 offset:4432
	ds_read_b128 v[170:173], v108 offset:4448
	ds_read_b128 v[174:177], v108 offset:4464
	ds_read_b128 v[178:181], v108 offset:8512
	ds_read_b128 v[182:185], v108 offset:8528
	ds_read_b128 v[186:189], v108 offset:8544
	ds_read_b128 v[190:193], v108 offset:8560
	s_waitcnt lgkmcnt(0)
	s_waitcnt vmcnt(31)
	v_fmac_f32_e32 v110, v210, v146
	v_fmac_f32_e32 v111, v210, v162
	v_fmac_f32_e32 v112, v210, v178
	global_load_dword v210, v[116:117], off nt
	v_lshl_add_u64 v[116:117], v[116:117], 0, s[8:9]
	s_waitcnt vmcnt(31)
	v_fmac_f32_e32 v110, v211, v147
	v_fmac_f32_e32 v111, v211, v163
	v_fmac_f32_e32 v112, v211, v179
	global_load_dword v211, v[116:117], off nt
	v_lshl_add_u64 v[116:117], v[116:117], 0, s[8:9]
	s_waitcnt vmcnt(31)
	v_fmac_f32_e32 v110, v212, v148
	v_fmac_f32_e32 v111, v212, v164
	v_fmac_f32_e32 v112, v212, v180
	global_load_dword v212, v[116:117], off nt
	v_lshl_add_u64 v[116:117], v[116:117], 0, s[8:9]
	s_waitcnt vmcnt(31)
	v_fmac_f32_e32 v110, v213, v149
	v_fmac_f32_e32 v111, v213, v165
	v_fmac_f32_e32 v112, v213, v181
	global_load_dword v213, v[116:117], off nt
	v_lshl_add_u64 v[116:117], v[116:117], 0, s[8:9]
	s_waitcnt vmcnt(31)
	v_fmac_f32_e32 v110, v214, v150
	v_fmac_f32_e32 v111, v214, v166
	v_fmac_f32_e32 v112, v214, v182
	global_load_dword v214, v[116:117], off nt
	v_lshl_add_u64 v[116:117], v[116:117], 0, s[8:9]
	s_waitcnt vmcnt(31)
	v_fmac_f32_e32 v110, v215, v151
	v_fmac_f32_e32 v111, v215, v167
	v_fmac_f32_e32 v112, v215, v183
	global_load_dword v215, v[116:117], off nt
	v_lshl_add_u64 v[116:117], v[116:117], 0, s[8:9]
	s_waitcnt vmcnt(31)
	v_fmac_f32_e32 v110, v216, v152
	v_fmac_f32_e32 v111, v216, v168
	v_fmac_f32_e32 v112, v216, v184
	global_load_dword v216, v[116:117], off nt
	v_lshl_add_u64 v[116:117], v[116:117], 0, s[8:9]
	s_waitcnt vmcnt(31)
	v_fmac_f32_e32 v110, v217, v153
	v_fmac_f32_e32 v111, v217, v169
	v_fmac_f32_e32 v112, v217, v185
	global_load_dword v217, v[116:117], off nt
	v_lshl_add_u64 v[116:117], v[116:117], 0, s[8:9]
	s_waitcnt vmcnt(31)
	v_fmac_f32_e32 v110, v218, v154
	v_fmac_f32_e32 v111, v218, v170
	v_fmac_f32_e32 v112, v218, v186
	global_load_dword v218, v[116:117], off nt
	v_lshl_add_u64 v[116:117], v[116:117], 0, s[8:9]
	s_waitcnt vmcnt(31)
	v_fmac_f32_e32 v110, v219, v155
	v_fmac_f32_e32 v111, v219, v171
	v_fmac_f32_e32 v112, v219, v187
	global_load_dword v219, v[116:117], off nt
	v_lshl_add_u64 v[116:117], v[116:117], 0, s[8:9]
	s_waitcnt vmcnt(31)
	v_fmac_f32_e32 v110, v220, v156
	v_fmac_f32_e32 v111, v220, v172
	v_fmac_f32_e32 v112, v220, v188
	global_load_dword v220, v[116:117], off nt
	v_lshl_add_u64 v[116:117], v[116:117], 0, s[8:9]
	s_waitcnt vmcnt(31)
	v_fmac_f32_e32 v110, v221, v157
	v_fmac_f32_e32 v111, v221, v173
	v_fmac_f32_e32 v112, v221, v189
	global_load_dword v221, v[116:117], off nt
	v_lshl_add_u64 v[116:117], v[116:117], 0, s[8:9]
	s_waitcnt vmcnt(31)
	v_fmac_f32_e32 v110, v222, v158
	v_fmac_f32_e32 v111, v222, v174
	v_fmac_f32_e32 v112, v222, v190
	global_load_dword v222, v[116:117], off nt
	v_lshl_add_u64 v[116:117], v[116:117], 0, s[8:9]
	s_waitcnt vmcnt(31)
	v_fmac_f32_e32 v110, v223, v159
	v_fmac_f32_e32 v111, v223, v175
	v_fmac_f32_e32 v112, v223, v191
	global_load_dword v223, v[116:117], off nt
	v_lshl_add_u64 v[116:117], v[116:117], 0, s[8:9]
	s_waitcnt vmcnt(31)
	v_fmac_f32_e32 v110, v224, v160
	v_fmac_f32_e32 v111, v224, v176
	v_fmac_f32_e32 v112, v224, v192
	global_load_dword v224, v[116:117], off nt
	v_lshl_add_u64 v[116:117], v[116:117], 0, s[8:9]
	s_waitcnt vmcnt(31)
	v_fmac_f32_e32 v110, v225, v161
	v_fmac_f32_e32 v111, v225, v177
	v_fmac_f32_e32 v112, v225, v193
	global_load_dword v225, v[116:117], off nt
	v_lshl_add_u64 v[116:117], v[116:117], 0, s[8:9]
	ds_read_b128 v[146:149], v108 offset:384
	ds_read_b128 v[150:153], v108 offset:400
	ds_read_b128 v[154:157], v108 offset:416
	ds_read_b128 v[158:161], v108 offset:432
	ds_read_b128 v[162:165], v108 offset:4480
	ds_read_b128 v[166:169], v108 offset:4496
	ds_read_b128 v[170:173], v108 offset:4512
	ds_read_b128 v[174:177], v108 offset:4528
	ds_read_b128 v[178:181], v108 offset:8576
	ds_read_b128 v[182:185], v108 offset:8592
	ds_read_b128 v[186:189], v108 offset:8608
	ds_read_b128 v[190:193], v108 offset:8624
	s_waitcnt lgkmcnt(0)
	s_waitcnt vmcnt(31)
	v_fmac_f32_e32 v110, v194, v146
	v_fmac_f32_e32 v111, v194, v162
	v_fmac_f32_e32 v112, v194, v178
	s_waitcnt vmcnt(30)
	v_fmac_f32_e32 v110, v195, v147
	v_fmac_f32_e32 v111, v195, v163
	v_fmac_f32_e32 v112, v195, v179
	s_waitcnt vmcnt(29)
	v_fmac_f32_e32 v110, v196, v148
	v_fmac_f32_e32 v111, v196, v164
	v_fmac_f32_e32 v112, v196, v180
	s_waitcnt vmcnt(28)
	v_fmac_f32_e32 v110, v197, v149
	v_fmac_f32_e32 v111, v197, v165
	v_fmac_f32_e32 v112, v197, v181
	s_waitcnt vmcnt(27)
	v_fmac_f32_e32 v110, v198, v150
	v_fmac_f32_e32 v111, v198, v166
	v_fmac_f32_e32 v112, v198, v182
	s_waitcnt vmcnt(26)
	v_fmac_f32_e32 v110, v199, v151
	v_fmac_f32_e32 v111, v199, v167
	v_fmac_f32_e32 v112, v199, v183
	s_waitcnt vmcnt(25)
	v_fmac_f32_e32 v110, v200, v152
	v_fmac_f32_e32 v111, v200, v168
	v_fmac_f32_e32 v112, v200, v184
	s_waitcnt vmcnt(24)
	v_fmac_f32_e32 v110, v201, v153
	v_fmac_f32_e32 v111, v201, v169
	v_fmac_f32_e32 v112, v201, v185
	s_waitcnt vmcnt(23)
	v_fmac_f32_e32 v110, v202, v154
	v_fmac_f32_e32 v111, v202, v170
	v_fmac_f32_e32 v112, v202, v186
	s_waitcnt vmcnt(22)
	v_fmac_f32_e32 v110, v203, v155
	v_fmac_f32_e32 v111, v203, v171
	v_fmac_f32_e32 v112, v203, v187
	s_waitcnt vmcnt(21)
	v_fmac_f32_e32 v110, v204, v156
	v_fmac_f32_e32 v111, v204, v172
	v_fmac_f32_e32 v112, v204, v188
	s_waitcnt vmcnt(20)
	v_fmac_f32_e32 v110, v205, v157
	v_fmac_f32_e32 v111, v205, v173
	v_fmac_f32_e32 v112, v205, v189
	s_waitcnt vmcnt(19)
	v_fmac_f32_e32 v110, v206, v158
	v_fmac_f32_e32 v111, v206, v174
	v_fmac_f32_e32 v112, v206, v190
	s_waitcnt vmcnt(18)
	v_fmac_f32_e32 v110, v207, v159
	v_fmac_f32_e32 v111, v207, v175
	v_fmac_f32_e32 v112, v207, v191
	s_waitcnt vmcnt(17)
	v_fmac_f32_e32 v110, v208, v160
	v_fmac_f32_e32 v111, v208, v176
	v_fmac_f32_e32 v112, v208, v192
	s_waitcnt vmcnt(16)
	v_fmac_f32_e32 v110, v209, v161
	v_fmac_f32_e32 v111, v209, v177
	v_fmac_f32_e32 v112, v209, v193
	ds_read_b128 v[146:149], v108 offset:448
	ds_read_b128 v[150:153], v108 offset:464
	ds_read_b128 v[154:157], v108 offset:480
	ds_read_b128 v[158:161], v108 offset:496
	ds_read_b128 v[162:165], v108 offset:4544
	ds_read_b128 v[166:169], v108 offset:4560
	ds_read_b128 v[170:173], v108 offset:4576
	ds_read_b128 v[174:177], v108 offset:4592
	ds_read_b128 v[178:181], v108 offset:8640
	ds_read_b128 v[182:185], v108 offset:8656
	ds_read_b128 v[186:189], v108 offset:8672
	ds_read_b128 v[190:193], v108 offset:8688
	s_waitcnt lgkmcnt(0)
	s_waitcnt vmcnt(15)
	v_fmac_f32_e32 v110, v210, v146
	v_fmac_f32_e32 v111, v210, v162
	v_fmac_f32_e32 v112, v210, v178
	s_waitcnt vmcnt(14)
	v_fmac_f32_e32 v110, v211, v147
	v_fmac_f32_e32 v111, v211, v163
	v_fmac_f32_e32 v112, v211, v179
	s_waitcnt vmcnt(13)
	v_fmac_f32_e32 v110, v212, v148
	v_fmac_f32_e32 v111, v212, v164
	v_fmac_f32_e32 v112, v212, v180
	s_waitcnt vmcnt(12)
	v_fmac_f32_e32 v110, v213, v149
	v_fmac_f32_e32 v111, v213, v165
	v_fmac_f32_e32 v112, v213, v181
	s_waitcnt vmcnt(11)
	v_fmac_f32_e32 v110, v214, v150
	v_fmac_f32_e32 v111, v214, v166
	v_fmac_f32_e32 v112, v214, v182
	s_waitcnt vmcnt(10)
	v_fmac_f32_e32 v110, v215, v151
	v_fmac_f32_e32 v111, v215, v167
	v_fmac_f32_e32 v112, v215, v183
	s_waitcnt vmcnt(9)
	v_fmac_f32_e32 v110, v216, v152
	v_fmac_f32_e32 v111, v216, v168
	v_fmac_f32_e32 v112, v216, v184
	s_waitcnt vmcnt(8)
	v_fmac_f32_e32 v110, v217, v153
	v_fmac_f32_e32 v111, v217, v169
	v_fmac_f32_e32 v112, v217, v185
	s_waitcnt vmcnt(7)
	v_fmac_f32_e32 v110, v218, v154
	v_fmac_f32_e32 v111, v218, v170
	v_fmac_f32_e32 v112, v218, v186
	s_waitcnt vmcnt(6)
	v_fmac_f32_e32 v110, v219, v155
	v_fmac_f32_e32 v111, v219, v171
	v_fmac_f32_e32 v112, v219, v187
	s_waitcnt vmcnt(5)
	v_fmac_f32_e32 v110, v220, v156
	v_fmac_f32_e32 v111, v220, v172
	v_fmac_f32_e32 v112, v220, v188
	s_waitcnt vmcnt(4)
	v_fmac_f32_e32 v110, v221, v157
	v_fmac_f32_e32 v111, v221, v173
	v_fmac_f32_e32 v112, v221, v189
	s_waitcnt vmcnt(3)
	v_fmac_f32_e32 v110, v222, v158
	v_fmac_f32_e32 v111, v222, v174
	v_fmac_f32_e32 v112, v222, v190
	s_waitcnt vmcnt(2)
	v_fmac_f32_e32 v110, v223, v159
	v_fmac_f32_e32 v111, v223, v175
	v_fmac_f32_e32 v112, v223, v191
	s_waitcnt vmcnt(1)
	v_fmac_f32_e32 v110, v224, v160
	v_fmac_f32_e32 v111, v224, v176
	v_fmac_f32_e32 v112, v224, v192
	s_waitcnt vmcnt(0)
	v_fmac_f32_e32 v110, v225, v161
	v_fmac_f32_e32 v111, v225, v177
	v_fmac_f32_e32 v112, v225, v193
	v_mul_u32_u24_e32 v109, 0x180, v113
	v_lshl_add_u32 v109, v114, 2, v109
	ds_write_b32 v109, v110 offset:12288
	ds_write_b32 v109, v111 offset:12416
	ds_write_b32 v109, v112 offset:12544
	s_waitcnt lgkmcnt(0)
	s_barrier
	v_cmp_gt_u32_e32 vcc, 0x60, v137
	s_and_saveexec_b64 s[14:15], vcc
	s_cbranch_execz .Lgvm1_skip
	s_lshl_b32 s16, s100, 7
	s_add_u32 s16, s16, 0x6000
	v_lshl_add_u32 v102, v114, 2, s16
	global_load_dword v103, v102, s[26:27]
	v_lshlrev_b32_e32 v104, 7, v113
	v_lshl_add_u32 v104, v114, 2, v104
	ds_read_b32 v146, v104 offset:12288
	ds_read_b32 v147, v104 offset:12672
	ds_read_b32 v148, v104 offset:13056
	ds_read_b32 v149, v104 offset:13440
	ds_read_b32 v150, v104 offset:13824
	ds_read_b32 v151, v104 offset:14208
	ds_read_b32 v152, v104 offset:14592
	ds_read_b32 v153, v104 offset:14976
	v_mul_u32_u24_e32 v105, 0x6000, v113
	v_add_u32_e32 v105, v105, v102
	s_add_u32 s12, s12, 0x2f9c000
	s_addc_u32 s13, s13, 0
	s_waitcnt vmcnt(0) lgkmcnt(0)
	v_add_f32_e32 v103, v103, v146
	v_add_f32_e32 v103, v103, v147
	v_add_f32_e32 v103, v103, v148
	v_add_f32_e32 v103, v103, v149
	v_add_f32_e32 v103, v103, v150
	v_add_f32_e32 v103, v103, v151
	v_add_f32_e32 v103, v103, v152
	v_add_f32_e32 v103, v103, v153
	global_store_dword v105, v103, s[12:13]
.Lgvm1_skip:
	s_or_b64 exec, exec, s[14:15]
	s_waitcnt vmcnt(0) lgkmcnt(0)
	s_barrier
